# v14 plus: first K-loop trip of each unit peeled with SrcC=0 on the first-touch MFMAs; the 128 accumulator-zeroing moves per unit removed
# speedup vs baseline: 1.0165x; 1.0039x over previous
; #define PG8_STAGE(bufoff, gbase, voff) do { _Pragma("unroll") for (int _i = 0; _i < 2; ++_i) \
;         __builtin_amdgcn_global_load_lds((const unsigned*)((const char*)(gbase) + (voff)[_i]), (LAS unsigned*)(lds + (bufoff) + ldsw + _i * 8192), 16, 0, 0); } while (0)
; #define PG8_LDA(dst, b, h) do { _Pragma("unroll") for (int m = 0; m < 4; ++m) _Pragma("unroll") for (int k = 0; k < 2; ++k) dst[m][k] = *(const LAS bf16x8*)(lds + PG8_SA(b, h) + aoff + m * 2048 + k * 1024); } while (0)
; #define PG8_LDB(dst, b, h) do { _Pragma("unroll") for (int n = 0; n < 2; ++n) _Pragma("unroll") for (int k = 0; k < 2; ++k) dst[n][k] = *(const LAS bf16x8*)(lds + PG8_SB(b, h) + boff + n * 2048 + k * 1024); } while (0)
; #define PG8_WAIT_V(n) asm volatile("s_waitcnt vmcnt(" #n ")" ::: "memory")
; #define PG8_WAIT_L(n) asm volatile("s_waitcnt lgkmcnt(" #n ")" ::: "memory")
; #define PG8_BAR __builtin_amdgcn_s_barrier()
; #define PG8_SCHED __builtin_amdgcn_sched_barrier(0)
; template <class Epi, class Sched>
; __device__ __forceinline__ void gemm_phase(LAS unsigned char* lds, const Gemm g, const Sched& S, const Epi& E) {
;     ...
;         const bool has_next = S.next(ui + 1, nxt);
;         const char* nA = has_next ? PG8_APANEL(nxt.pm) : cA; const char* nB = has_next ? (const char*)g.Bt + (size_t)nxt.pn * tstep : cB;
;         for (int t = 0; t < nt; t += 2) {
;             const bool last = (t == nt - 2);
;             const char* a1 = cA + (size_t)(t + 1) * kstep;
;             const char* a2 = last ? nA : cA + (size_t)(t + 2) * kstep; const char* b2 = last ? nB : cB + (size_t)(t + 2) * kstep;
;             const char* a3 = a2 + kstep; const char* b3 = b2 + kstep;
;             PG8_LDB(B0, 0, 0); PG8_SCHED; PG8_LDA(At, 0, 0); PG8_STAGE(PG8_SA(1, 1), a1 + hstep, voffA);
;             PG8_WAIT_L(8); PG8_BAR; PG8_WAIT_L(0); PG8_MMA(0, 0, At, B0); PG8_BAR; PG8_SCHED;
;             PG8_LDB(B1, 0, 1); PG8_STAGE(PG8_SB(0, 0), b2, voffB);
;             PG8_BAR; PG8_WAIT_L(0); PG8_MMA(0, 1, At, B1); PG8_BAR;
;             PG8_LDA(At, 0, 1); PG8_STAGE(PG8_SA(0, 0), a2, voffA);
;             PG8_BAR; PG8_WAIT_L(0); PG8_MMA(1, 0, At, B0); PG8_BAR; PG8_SCHED;
;             PG8_STAGE(PG8_SB(0, 1), b2 + hstep, voffB);
;             PG8_WAIT_V(6); PG8_BAR; PG8_MMA(1, 1, At, B1); PG8_BAR;
.LBB0_164:
	s_cmp_lt_i32 s44, 0x100000
	s_cselect_b32 s24, s20, 0xffffff80
	s_cselect_b32 s25, s11, 0
	s_ashr_i32 s45, s44, 31
	s_lshl_b64 s[34:35], s[44:45], 19
	v_cmp_lt_i64_e32 vcc, s[46:47], v[152:153]
	s_add_u32 s46, s25, s34
	s_addc_u32 s47, s24, s35
	s_and_b64 s[34:35], vcc, exec
	s_cselect_b32 s34, s47, s49
	s_cselect_b32 s45, s46, s48
	s_ashr_i32 s43, s42, 31
	s_lshl_b64 s[60:61], s[42:43], 19
	s_add_u32 s76, s16, s60
	s_addc_u32 s77, s92, s61
	s_and_b64 s[60:61], vcc, exec
	s_cselect_b32 s43, s77, s39
	s_cselect_b32 s79, s76, s38
	s_add_u32 vcc_lo, s38, 0x100
	s_addc_u32 s35, s39, 0
	s_add_u32 s38, s48, 0x40080
	s_addc_u32 s39, s49, 0
	s_mov_b32 s50, -2
	v_add_u32_e32 v249, 0x10000, v167
	ds_read_b128 v[142:145], v249
	ds_read_b128 v[162:165], v249 offset:1024
	ds_read_b128 v[182:185], v249 offset:2048
	ds_read_b128 v[186:189], v249 offset:3072
	ds_read_b128 v[190:193], v169
	ds_read_b128 v[194:197], v169 offset:1024
	ds_read_b128 v[198:201], v169 offset:2048
	ds_read_b128 v[202:205], v169 offset:3072
	ds_read_b128 v[206:209], v169 offset:4096
	ds_read_b128 v[210:213], v169 offset:5120
	s_add_u32 s24, s38, 0xfffc0080
	s_addc_u32 s25, s39, -1
	s_add_i32 vcc_hi, 0, 0x10000
	s_cmp_eq_u32 s50, 12
	s_cselect_b32 s61, s34, s25
	s_cselect_b32 s60, s45, s24
	s_cselect_b32 s49, s43, s35
	s_cselect_b32 s48, s79, vcc_lo
	s_add_i32 m0, s93, 0xc000
	ds_read_b128 v[214:217], v169 offset:6144
	ds_read_b128 v[218:221], v169 offset:7168
	global_load_lds_dwordx4 v140, s[38:39]
	s_add_i32 m0, s93, 0xe000
	s_nop 0
	global_load_lds_dwordx4 v138, s[38:39]
	s_waitcnt lgkmcnt(8)
	s_barrier
	s_waitcnt lgkmcnt(0)
	s_setprio 1
	s_waitcnt lgkmcnt(0)
	v_mfma_f32_16x16x32_bf16 v[126:129], v[142:145], v[190:193], 0
	v_mfma_f32_16x16x32_bf16 v[126:129], v[162:165], v[194:197], v[126:129]
	v_mfma_f32_16x16x32_bf16 v[122:125], v[182:185], v[190:193], 0
	v_mfma_f32_16x16x32_bf16 v[122:125], v[186:189], v[194:197], v[122:125]
	v_mfma_f32_16x16x32_bf16 v[110:113], v[142:145], v[198:201], 0
	v_mfma_f32_16x16x32_bf16 v[110:113], v[162:165], v[202:205], v[110:113]
	v_mfma_f32_16x16x32_bf16 v[106:109], v[182:185], v[198:201], 0
	v_mfma_f32_16x16x32_bf16 v[106:109], v[186:189], v[202:205], v[106:109]
	v_mfma_f32_16x16x32_bf16 v[94:97], v[142:145], v[206:209], 0
	v_mfma_f32_16x16x32_bf16 v[94:97], v[162:165], v[210:213], v[94:97]
	v_mfma_f32_16x16x32_bf16 v[90:93], v[182:185], v[206:209], 0
	v_mfma_f32_16x16x32_bf16 v[90:93], v[186:189], v[210:213], v[90:93]
	v_mfma_f32_16x16x32_bf16 v[78:81], v[142:145], v[214:217], 0
	v_mfma_f32_16x16x32_bf16 v[78:81], v[162:165], v[218:221], v[78:81]
	v_mfma_f32_16x16x32_bf16 v[74:77], v[182:185], v[214:217], 0
	s_barrier
	v_mfma_f32_16x16x32_bf16 v[74:77], v[186:189], v[218:221], v[74:77]
	s_setprio 0
	s_add_i32 s51, 0, 0x14000
	s_add_i32 s24, vcc_hi, s86
	s_mov_b32 m0, s24
	ds_read_b128 v[222:225], v249 offset:16384
	ds_read_b128 v[226:229], v249 offset:17408
	ds_read_b128 v[230:233], v249 offset:18432
	ds_read_b128 v[234:237], v249 offset:19456
	global_load_lds_dwordx4 v134, s[48:49]
	s_add_i32 m0, s24, 0x2000
	s_nop 0
	global_load_lds_dwordx4 v130, s[48:49]
	s_barrier
	s_waitcnt lgkmcnt(0)
	s_setprio 1
	s_waitcnt lgkmcnt(0)
	v_mfma_f32_16x16x32_bf16 v[118:121], v[222:225], v[190:193], 0
	v_mfma_f32_16x16x32_bf16 v[118:121], v[226:229], v[194:197], v[118:121]
	v_mfma_f32_16x16x32_bf16 v[114:117], v[230:233], v[190:193], 0
	v_mfma_f32_16x16x32_bf16 v[114:117], v[234:237], v[194:197], v[114:117]
	v_mfma_f32_16x16x32_bf16 v[102:105], v[222:225], v[198:201], 0
	v_mfma_f32_16x16x32_bf16 v[102:105], v[226:229], v[202:205], v[102:105]
	v_mfma_f32_16x16x32_bf16 v[98:101], v[230:233], v[198:201], 0
	v_mfma_f32_16x16x32_bf16 v[98:101], v[234:237], v[202:205], v[98:101]
	v_mfma_f32_16x16x32_bf16 v[86:89], v[222:225], v[206:209], 0
	v_mfma_f32_16x16x32_bf16 v[86:89], v[226:229], v[210:213], v[86:89]
	v_mfma_f32_16x16x32_bf16 v[82:85], v[230:233], v[206:209], 0
	v_mfma_f32_16x16x32_bf16 v[82:85], v[234:237], v[210:213], v[82:85]
	v_mfma_f32_16x16x32_bf16 v[70:73], v[222:225], v[214:217], 0
	v_mfma_f32_16x16x32_bf16 v[70:73], v[226:229], v[218:221], v[70:73]
	v_mfma_f32_16x16x32_bf16 v[66:69], v[230:233], v[214:217], 0
	s_barrier
	v_mfma_f32_16x16x32_bf16 v[66:69], v[234:237], v[218:221], v[66:69]
	s_setprio 0
	s_mov_b32 m0, s93
	s_mov_b64 s[100:101], s[60:61]
	ds_read_b128 v[190:193], v169 offset:16384
	ds_read_b128 v[194:197], v169 offset:17408
	ds_read_b128 v[198:201], v169 offset:18432
	ds_read_b128 v[202:205], v169 offset:19456
	ds_read_b128 v[206:209], v169 offset:20480
	ds_read_b128 v[210:213], v169 offset:21504
	ds_read_b128 v[214:217], v169 offset:22528
	ds_read_b128 v[218:221], v169 offset:23552
	global_load_lds_dwordx4 v136, s[60:61]
	s_mov_b64 s[100:101], s[60:61]
	s_mov_b32 m0, s98
	s_nop 0
	global_load_lds_dwordx4 v132, s[60:61]
	s_waitcnt vmcnt(8)
	s_barrier
	s_waitcnt lgkmcnt(0)
	s_setprio 1
	s_waitcnt lgkmcnt(0)
	v_mfma_f32_16x16x32_bf16 v[62:65], v[142:145], v[190:193], 0
	v_mfma_f32_16x16x32_bf16 v[62:65], v[162:165], v[194:197], v[62:65]
	v_mfma_f32_16x16x32_bf16 v[58:61], v[182:185], v[190:193], 0
	v_mfma_f32_16x16x32_bf16 v[58:61], v[186:189], v[194:197], v[58:61]
	v_mfma_f32_16x16x32_bf16 v[46:49], v[142:145], v[198:201], 0
	v_mfma_f32_16x16x32_bf16 v[46:49], v[162:165], v[202:205], v[46:49]
	v_mfma_f32_16x16x32_bf16 v[42:45], v[182:185], v[198:201], 0
	v_mfma_f32_16x16x32_bf16 v[42:45], v[186:189], v[202:205], v[42:45]
	v_mfma_f32_16x16x32_bf16 v[30:33], v[142:145], v[206:209], 0
	v_mfma_f32_16x16x32_bf16 v[30:33], v[162:165], v[210:213], v[30:33]
	v_mfma_f32_16x16x32_bf16 v[26:29], v[182:185], v[206:209], 0
	v_mfma_f32_16x16x32_bf16 v[26:29], v[186:189], v[210:213], v[26:29]
	v_mfma_f32_16x16x32_bf16 v[14:17], v[142:145], v[214:217], 0
	v_mfma_f32_16x16x32_bf16 v[14:17], v[162:165], v[218:221], v[14:17]
	v_mfma_f32_16x16x32_bf16 v[10:13], v[182:185], v[214:217], 0
	s_barrier
; #define PG8_STAGE(bufoff, gbase, voff) do { _Pragma("unroll") for (int _i = 0; _i < 2; ++_i) \
;         __builtin_amdgcn_global_load_lds((const unsigned*)((const char*)(gbase) + (voff)[_i]), (LAS unsigned*)(lds + (bufoff) + ldsw + _i * 8192), 16, 0, 0); } while (0)
; #define PG8_LDA(dst, b, h) do { _Pragma("unroll") for (int m = 0; m < 4; ++m) _Pragma("unroll") for (int k = 0; k < 2; ++k) dst[m][k] = *(const LAS bf16x8*)(lds + PG8_SA(b, h) + aoff + m * 2048 + k * 1024); } while (0)
; #define PG8_LDB(dst, b, h) do { _Pragma("unroll") for (int n = 0; n < 2; ++n) _Pragma("unroll") for (int k = 0; k < 2; ++k) dst[n][k] = *(const LAS bf16x8*)(lds + PG8_SB(b, h) + boff + n * 2048 + k * 1024); } while (0)
; #define PG8_MMA(ai, bj, At, Bt) do { __builtin_amdgcn_s_setprio(1); _Pragma("unroll") for (int m = 0; m < 4; ++m) _Pragma("unroll") for (int n = 0; n < 2; ++n) _Pragma("unroll") for (int k = 0; k < 2; ++k) \
;         acc[ai][bj][m][n] = __builtin_amdgcn_mfma_f32_16x16x32_bf16(Bt[n][k], At[m][k], acc[ai][bj][m][n], 0, 0, 0); __builtin_amdgcn_s_setprio(0); } while (0)
; #define PG8_WAIT_V(n) asm volatile("s_waitcnt vmcnt(" #n ")" ::: "memory")
; #define PG8_WAIT_L(n) asm volatile("s_waitcnt lgkmcnt(" #n ")" ::: "memory")
; #define PG8_BAR __builtin_amdgcn_s_barrier()
; #define PG8_SCHED __builtin_amdgcn_sched_barrier(0)
; template <class Epi, class Sched>
; __device__ __forceinline__ void gemm_phase(LAS unsigned char* lds, const Gemm g, const Sched& S, const Epi& E) {
;     ...
;             PG8_WAIT_V(6); PG8_BAR; PG8_MMA(1, 1, At, B1); PG8_BAR;
;             PG8_LDB(B0, 1, 0); PG8_SCHED; PG8_LDA(At, 1, 0); PG8_STAGE(PG8_SA(0, 1), a2 + hstep, voffA);
;             PG8_WAIT_L(8); PG8_BAR; PG8_WAIT_L(0); PG8_MMA(0, 0, At, B0); PG8_BAR; PG8_SCHED;
;             PG8_LDB(B1, 1, 1); PG8_STAGE(PG8_SB(1, 0), b3, voffB);
;             PG8_BAR; PG8_WAIT_L(0); PG8_MMA(0, 1, At, B1); PG8_BAR;
;             PG8_LDA(At, 1, 1); PG8_STAGE(PG8_SA(1, 0), a3, voffA);
;             PG8_BAR; PG8_WAIT_L(0); PG8_MMA(1, 0, At, B0); PG8_BAR; PG8_SCHED;
	v_mfma_f32_16x16x32_bf16 v[10:13], v[186:189], v[218:221], v[10:13]
	s_setprio 0
	s_add_u32 s24, s48, 0x40000
	s_addc_u32 s25, s49, 0
	s_add_i32 s51, s51, s86
	s_mov_b32 m0, s51
	s_nop 0
	global_load_lds_dwordx4 v134, s[24:25]
	s_add_i32 m0, s51, 0x2000
	s_nop 0
	global_load_lds_dwordx4 v130, s[24:25]
	s_waitcnt vmcnt(6)
	s_barrier
	s_setprio 1
	v_mfma_f32_16x16x32_bf16 v[54:57], v[222:225], v[190:193], 0
	ds_read_b128 v[142:145], v249 offset:32768
	ds_read_b128 v[162:165], v249 offset:33792
	v_mfma_f32_16x16x32_bf16 v[54:57], v[226:229], v[194:197], v[54:57]
	ds_read_b128 v[182:185], v249 offset:34816
	ds_read_b128 v[186:189], v249 offset:35840
	v_mfma_f32_16x16x32_bf16 v[50:53], v[230:233], v[190:193], 0
	ds_read_b128 v[190:193], v169 offset:32768
	v_mfma_f32_16x16x32_bf16 v[50:53], v[234:237], v[194:197], v[50:53]
	ds_read_b128 v[194:197], v169 offset:33792
	v_mfma_f32_16x16x32_bf16 v[38:41], v[222:225], v[198:201], 0
	v_mfma_f32_16x16x32_bf16 v[38:41], v[226:229], v[202:205], v[38:41]
	v_mfma_f32_16x16x32_bf16 v[34:37], v[230:233], v[198:201], 0
	ds_read_b128 v[198:201], v169 offset:34816
	v_mfma_f32_16x16x32_bf16 v[34:37], v[234:237], v[202:205], v[34:37]
	ds_read_b128 v[202:205], v169 offset:35840
	v_mfma_f32_16x16x32_bf16 v[22:25], v[222:225], v[206:209], 0
	v_mfma_f32_16x16x32_bf16 v[22:25], v[226:229], v[210:213], v[22:25]
	v_mfma_f32_16x16x32_bf16 v[18:21], v[230:233], v[206:209], 0
	ds_read_b128 v[206:209], v169 offset:36864
	v_mfma_f32_16x16x32_bf16 v[18:21], v[234:237], v[210:213], v[18:21]
	ds_read_b128 v[210:213], v169 offset:37888
	v_mfma_f32_16x16x32_bf16 v[6:9], v[222:225], v[214:217], 0
	v_mfma_f32_16x16x32_bf16 v[6:9], v[226:229], v[218:221], v[6:9]
	v_mfma_f32_16x16x32_bf16 v[2:5], v[230:233], v[214:217], 0
	s_barrier
	v_mfma_f32_16x16x32_bf16 v[2:5], v[234:237], v[218:221], v[2:5]
	s_setprio 0
	s_add_i32 s51, 0, 0x18000
	s_add_u32 s24, s60, 0x40000
	s_addc_u32 s25, s61, 0
	s_mov_b32 m0, s99
	ds_read_b128 v[214:217], v169 offset:38912
	ds_read_b128 v[218:221], v169 offset:39936
	global_load_lds_dwordx4 v136, s[24:25]
	s_mov_b32 m0, s94
	s_nop 0
	global_load_lds_dwordx4 v132, s[24:25]
	s_waitcnt lgkmcnt(8)
	s_barrier
	s_waitcnt lgkmcnt(0)
	s_setprio 1
	s_waitcnt lgkmcnt(0)
	v_mfma_f32_16x16x32_bf16 v[126:129], v[142:145], v[190:193], v[126:129]
	v_mfma_f32_16x16x32_bf16 v[126:129], v[162:165], v[194:197], v[126:129]
	v_mfma_f32_16x16x32_bf16 v[122:125], v[182:185], v[190:193], v[122:125]
	v_mfma_f32_16x16x32_bf16 v[122:125], v[186:189], v[194:197], v[122:125]
	v_mfma_f32_16x16x32_bf16 v[110:113], v[142:145], v[198:201], v[110:113]
	v_mfma_f32_16x16x32_bf16 v[110:113], v[162:165], v[202:205], v[110:113]
	v_mfma_f32_16x16x32_bf16 v[106:109], v[182:185], v[198:201], v[106:109]
	v_mfma_f32_16x16x32_bf16 v[106:109], v[186:189], v[202:205], v[106:109]
	v_mfma_f32_16x16x32_bf16 v[94:97], v[142:145], v[206:209], v[94:97]
	v_mfma_f32_16x16x32_bf16 v[94:97], v[162:165], v[210:213], v[94:97]
	v_mfma_f32_16x16x32_bf16 v[90:93], v[182:185], v[206:209], v[90:93]
	v_mfma_f32_16x16x32_bf16 v[90:93], v[186:189], v[210:213], v[90:93]
	v_mfma_f32_16x16x32_bf16 v[78:81], v[142:145], v[214:217], v[78:81]
	v_mfma_f32_16x16x32_bf16 v[78:81], v[162:165], v[218:221], v[78:81]
	v_mfma_f32_16x16x32_bf16 v[74:77], v[182:185], v[214:217], v[74:77]
	s_barrier
	v_mfma_f32_16x16x32_bf16 v[74:77], v[186:189], v[218:221], v[74:77]
	s_setprio 0
	s_add_i32 s60, 0, 0x1c000
	s_add_i32 s24, s51, s86
	s_add_i32 m0, s24, 0xffffff80
	ds_read_b128 v[222:225], v249 offset:49152
	ds_read_b128 v[226:229], v249 offset:50176
	ds_read_b128 v[230:233], v249 offset:51200
	ds_read_b128 v[234:237], v249 offset:52224
	global_load_lds_dwordx4 v134, s[48:49] offset:128
	s_add_i32 m0, s24, 0x1f80
	s_nop 0
	global_load_lds_dwordx4 v130, s[48:49] offset:128
	s_barrier
; #define PG8_STAGE(bufoff, gbase, voff) do { _Pragma("unroll") for (int _i = 0; _i < 2; ++_i) \
;         __builtin_amdgcn_global_load_lds((const unsigned*)((const char*)(gbase) + (voff)[_i]), (LAS unsigned*)(lds + (bufoff) + ldsw + _i * 8192), 16, 0, 0); } while (0)
; #define PG8_LDA(dst, b, h) do { _Pragma("unroll") for (int m = 0; m < 4; ++m) _Pragma("unroll") for (int k = 0; k < 2; ++k) dst[m][k] = *(const LAS bf16x8*)(lds + PG8_SA(b, h) + aoff + m * 2048 + k * 1024); } while (0)
; #define PG8_LDB(dst, b, h) do { _Pragma("unroll") for (int n = 0; n < 2; ++n) _Pragma("unroll") for (int k = 0; k < 2; ++k) dst[n][k] = *(const LAS bf16x8*)(lds + PG8_SB(b, h) + boff + n * 2048 + k * 1024); } while (0)
; #define PG8_MMA(ai, bj, At, Bt) do { __builtin_amdgcn_s_setprio(1); _Pragma("unroll") for (int m = 0; m < 4; ++m) _Pragma("unroll") for (int n = 0; n < 2; ++n) _Pragma("unroll") for (int k = 0; k < 2; ++k) \
;         acc[ai][bj][m][n] = __builtin_amdgcn_mfma_f32_16x16x32_bf16(Bt[n][k], At[m][k], acc[ai][bj][m][n], 0, 0, 0); __builtin_amdgcn_s_setprio(0); } while (0)
; #define PG8_WAIT_V(n) asm volatile("s_waitcnt vmcnt(" #n ")" ::: "memory")
; #define PG8_WAIT_L(n) asm volatile("s_waitcnt lgkmcnt(" #n ")" ::: "memory")
; #define PG8_BAR __builtin_amdgcn_s_barrier()
; #define PG8_SCHED __builtin_amdgcn_sched_barrier(0)
; template <class Epi, class Sched>
; __device__ __forceinline__ void gemm_phase(LAS unsigned char* lds, const Gemm g, const Sched& S, const Epi& E) {
;     ...
;             PG8_WAIT_L(8); PG8_BAR; PG8_WAIT_L(0); PG8_MMA(0, 0, At, B0); PG8_BAR; PG8_SCHED;
;             PG8_LDB(B1, 1, 1); PG8_STAGE(PG8_SB(1, 0), b3, voffB);
;             PG8_BAR; PG8_WAIT_L(0); PG8_MMA(0, 1, At, B1); PG8_BAR;
;             PG8_LDA(At, 1, 1); PG8_STAGE(PG8_SA(1, 0), a3, voffA);
;             PG8_BAR; PG8_WAIT_L(0); PG8_MMA(1, 0, At, B0); PG8_BAR; PG8_SCHED;
;             PG8_STAGE(PG8_SB(1, 1), b3 + hstep, voffB);
;             PG8_WAIT_V(6); PG8_BAR; PG8_MMA(1, 1, At, B1); PG8_BAR;
;         }
	s_waitcnt lgkmcnt(0)
	s_setprio 1
	s_waitcnt lgkmcnt(0)
	v_mfma_f32_16x16x32_bf16 v[118:121], v[222:225], v[190:193], v[118:121]
	v_mfma_f32_16x16x32_bf16 v[118:121], v[226:229], v[194:197], v[118:121]
	v_mfma_f32_16x16x32_bf16 v[114:117], v[230:233], v[190:193], v[114:117]
	v_mfma_f32_16x16x32_bf16 v[114:117], v[234:237], v[194:197], v[114:117]
	v_mfma_f32_16x16x32_bf16 v[102:105], v[222:225], v[198:201], v[102:105]
	v_mfma_f32_16x16x32_bf16 v[102:105], v[226:229], v[202:205], v[102:105]
	v_mfma_f32_16x16x32_bf16 v[98:101], v[230:233], v[198:201], v[98:101]
	v_mfma_f32_16x16x32_bf16 v[98:101], v[234:237], v[202:205], v[98:101]
	v_mfma_f32_16x16x32_bf16 v[86:89], v[222:225], v[206:209], v[86:89]
	v_mfma_f32_16x16x32_bf16 v[86:89], v[226:229], v[210:213], v[86:89]
	v_mfma_f32_16x16x32_bf16 v[82:85], v[230:233], v[206:209], v[82:85]
	v_mfma_f32_16x16x32_bf16 v[82:85], v[234:237], v[210:213], v[82:85]
	v_mfma_f32_16x16x32_bf16 v[70:73], v[222:225], v[214:217], v[70:73]
	v_mfma_f32_16x16x32_bf16 v[70:73], v[226:229], v[218:221], v[70:73]
	v_mfma_f32_16x16x32_bf16 v[66:69], v[230:233], v[214:217], v[66:69]
	s_barrier
	v_mfma_f32_16x16x32_bf16 v[66:69], v[234:237], v[218:221], v[66:69]
	s_setprio 0
	s_add_i32 m0, s95, 0xffffff80
	ds_read_b128 v[190:193], v169 offset:49152
	ds_read_b128 v[194:197], v169 offset:50176
	ds_read_b128 v[198:201], v169 offset:51200
	ds_read_b128 v[202:205], v169 offset:52224
	ds_read_b128 v[206:209], v169 offset:53248
	ds_read_b128 v[210:213], v169 offset:54272
	ds_read_b128 v[214:217], v169 offset:55296
	ds_read_b128 v[218:221], v169 offset:56320
	global_load_lds_dwordx4 v136, s[100:101] offset:128
	s_add_i32 m0, s96, 0xffffff80
	s_nop 0
	global_load_lds_dwordx4 v132, s[100:101] offset:128
	s_waitcnt vmcnt(8)
	s_barrier
	s_waitcnt lgkmcnt(0)
	s_setprio 1
	s_waitcnt lgkmcnt(0)
	v_mfma_f32_16x16x32_bf16 v[62:65], v[142:145], v[190:193], v[62:65]
	v_mfma_f32_16x16x32_bf16 v[62:65], v[162:165], v[194:197], v[62:65]
	v_mfma_f32_16x16x32_bf16 v[58:61], v[182:185], v[190:193], v[58:61]
	v_mfma_f32_16x16x32_bf16 v[58:61], v[186:189], v[194:197], v[58:61]
	v_mfma_f32_16x16x32_bf16 v[46:49], v[142:145], v[198:201], v[46:49]
	v_mfma_f32_16x16x32_bf16 v[46:49], v[162:165], v[202:205], v[46:49]
	v_mfma_f32_16x16x32_bf16 v[42:45], v[182:185], v[198:201], v[42:45]
	v_mfma_f32_16x16x32_bf16 v[42:45], v[186:189], v[202:205], v[42:45]
	v_mfma_f32_16x16x32_bf16 v[30:33], v[142:145], v[206:209], v[30:33]
	v_mfma_f32_16x16x32_bf16 v[30:33], v[162:165], v[210:213], v[30:33]
	v_mfma_f32_16x16x32_bf16 v[26:29], v[182:185], v[206:209], v[26:29]
	v_mfma_f32_16x16x32_bf16 v[26:29], v[186:189], v[210:213], v[26:29]
	v_mfma_f32_16x16x32_bf16 v[14:17], v[142:145], v[214:217], v[14:17]
	v_mfma_f32_16x16x32_bf16 v[14:17], v[162:165], v[218:221], v[14:17]
	v_mfma_f32_16x16x32_bf16 v[10:13], v[182:185], v[214:217], v[10:13]
	s_barrier
	v_mfma_f32_16x16x32_bf16 v[10:13], v[186:189], v[218:221], v[10:13]
	s_setprio 0
	s_add_u32 s24, s48, 0x40080
	s_addc_u32 s25, s49, 0
	s_add_i32 s48, s60, s86
	s_mov_b32 m0, s48
	s_nop 0
	global_load_lds_dwordx4 v134, s[24:25]
	s_add_i32 m0, s48, 0x2000
	s_nop 0
	global_load_lds_dwordx4 v130, s[24:25]
	s_waitcnt vmcnt(6)
	s_barrier
	s_setprio 1
	v_mfma_f32_16x16x32_bf16 v[54:57], v[222:225], v[190:193], v[54:57]
	ds_read_b128 v[142:145], v249
	ds_read_b128 v[162:165], v249 offset:1024
	v_mfma_f32_16x16x32_bf16 v[54:57], v[226:229], v[194:197], v[54:57]
	ds_read_b128 v[182:185], v249 offset:2048
	ds_read_b128 v[186:189], v249 offset:3072
	v_mfma_f32_16x16x32_bf16 v[50:53], v[230:233], v[190:193], v[50:53]
	ds_read_b128 v[190:193], v169
	v_mfma_f32_16x16x32_bf16 v[50:53], v[234:237], v[194:197], v[50:53]
	ds_read_b128 v[194:197], v169 offset:1024
	v_mfma_f32_16x16x32_bf16 v[38:41], v[222:225], v[198:201], v[38:41]
	v_mfma_f32_16x16x32_bf16 v[38:41], v[226:229], v[202:205], v[38:41]
	v_mfma_f32_16x16x32_bf16 v[34:37], v[230:233], v[198:201], v[34:37]
	ds_read_b128 v[198:201], v169 offset:2048
	v_mfma_f32_16x16x32_bf16 v[34:37], v[234:237], v[202:205], v[34:37]
	ds_read_b128 v[202:205], v169 offset:3072
	v_mfma_f32_16x16x32_bf16 v[22:25], v[222:225], v[206:209], v[22:25]
	v_mfma_f32_16x16x32_bf16 v[22:25], v[226:229], v[210:213], v[22:25]
	v_mfma_f32_16x16x32_bf16 v[18:21], v[230:233], v[206:209], v[18:21]
	ds_read_b128 v[206:209], v169 offset:4096
	v_mfma_f32_16x16x32_bf16 v[18:21], v[234:237], v[210:213], v[18:21]
	ds_read_b128 v[210:213], v169 offset:5120
	v_mfma_f32_16x16x32_bf16 v[6:9], v[222:225], v[214:217], v[6:9]
	v_mfma_f32_16x16x32_bf16 v[6:9], v[226:229], v[218:221], v[6:9]
	v_mfma_f32_16x16x32_bf16 v[2:5], v[230:233], v[214:217], v[2:5]
	s_barrier
	v_mfma_f32_16x16x32_bf16 v[2:5], v[234:237], v[218:221], v[2:5]
	s_setprio 0
	s_add_i32 s50, s50, 2
	s_add_u32 vcc_lo, vcc_lo, 0x100
	s_addc_u32 s35, s35, 0
	s_add_u32 s38, s38, 0x100
	s_addc_u32 s39, s39, 0
	s_cmp_gt_u32 s50, 13

; #define PG8_STAGE(bufoff, gbase, voff) do { _Pragma("unroll") for (int _i = 0; _i < 2; ++_i) \
;         __builtin_amdgcn_global_load_lds((const unsigned*)((const char*)(gbase) + (voff)[_i]), (LAS unsigned*)(lds + (bufoff) + ldsw + _i * 8192), 16, 0, 0); } while (0)
; #define PG8_LDA(dst, b, h) do { _Pragma("unroll") for (int m = 0; m < 4; ++m) _Pragma("unroll") for (int k = 0; k < 2; ++k) dst[m][k] = *(const LAS bf16x8*)(lds + PG8_SA(b, h) + aoff + m * 2048 + k * 1024); } while (0)
; #define PG8_LDB(dst, b, h) do { _Pragma("unroll") for (int n = 0; n < 2; ++n) _Pragma("unroll") for (int k = 0; k < 2; ++k) dst[n][k] = *(const LAS bf16x8*)(lds + PG8_SB(b, h) + boff + n * 2048 + k * 1024); } while (0)
; #define PG8_WAIT_V(n) asm volatile("s_waitcnt vmcnt(" #n ")" ::: "memory")
; #define PG8_WAIT_L(n) asm volatile("s_waitcnt lgkmcnt(" #n ")" ::: "memory")
; #define PG8_BAR __builtin_amdgcn_s_barrier()
; #define PG8_SCHED __builtin_amdgcn_sched_barrier(0)
; template <class Epi, class Sched>
; __device__ __forceinline__ void gemm_phase(LAS unsigned char* lds, const Gemm g, const Sched& S, const Epi& E) {
;     ...
;         const bool has_next = S.next(ui + 1, nxt);
;         const char* nA = has_next ? PG8_APANEL(nxt.pm) : cA; const char* nB = has_next ? (const char*)g.Bt + (size_t)nxt.pn * tstep : cB;
;         for (int t = 0; t < nt; t += 2) {
;             const bool last = (t == nt - 2);
;             const char* a1 = cA + (size_t)(t + 1) * kstep;
;             const char* a2 = last ? nA : cA + (size_t)(t + 2) * kstep; const char* b2 = last ? nB : cB + (size_t)(t + 2) * kstep;
;             const char* a3 = a2 + kstep; const char* b3 = b2 + kstep;
;             PG8_LDB(B0, 0, 0); PG8_SCHED; PG8_LDA(At, 0, 0); PG8_STAGE(PG8_SA(1, 1), a1 + hstep, voffA);
;             PG8_WAIT_L(8); PG8_BAR; PG8_WAIT_L(0); PG8_MMA(0, 0, At, B0); PG8_BAR; PG8_SCHED;
;             PG8_LDB(B1, 0, 1); PG8_STAGE(PG8_SB(0, 0), b2, voffB);
;             PG8_BAR; PG8_WAIT_L(0); PG8_MMA(0, 1, At, B1); PG8_BAR;
;             PG8_LDA(At, 0, 1); PG8_STAGE(PG8_SA(0, 0), a2, voffA);
;             PG8_BAR; PG8_WAIT_L(0); PG8_MMA(1, 0, At, B0); PG8_BAR; PG8_SCHED;
;             PG8_STAGE(PG8_SB(0, 1), b2 + hstep, voffB);
;             PG8_WAIT_V(6); PG8_BAR; PG8_MMA(1, 1, At, B1); PG8_BAR;
.LBB0_415:
	s_ashr_i32 s47, s46, 31
	s_lshl_b64 s[24:25], s[46:47], 19
	s_add_u32 s48, s82, s24
	s_addc_u32 s49, s83, s25
	s_and_b64 s[0:1], s[0:1], exec
	s_cselect_b32 s47, s49, s37
	s_cselect_b32 s61, s48, s36
	s_add_u32 s35, s36, 0x100
	s_addc_u32 s50, s37, 0
	s_add_u32 s0, s38, 0x40080
	s_addc_u32 s1, s39, 0
	s_mov_b32 s38, -2
	v_add_u32_e32 v249, 0x10000, v144
	ds_read_b128 v[164:167], v249
	ds_read_b128 v[182:185], v249 offset:1024
	ds_read_b128 v[186:189], v249 offset:2048
	ds_read_b128 v[190:193], v249 offset:3072
	ds_read_b128 v[194:197], v162
	ds_read_b128 v[198:201], v162 offset:1024
	ds_read_b128 v[202:205], v162 offset:2048
	ds_read_b128 v[206:209], v162 offset:3072
	ds_read_b128 v[210:213], v162 offset:4096
	ds_read_b128 v[214:217], v162 offset:5120
	s_add_u32 s24, s0, 0xfffc0080
	s_addc_u32 s25, s1, -1
	s_add_i32 s39, 0, 0x10000
	s_cmp_eq_u32 s38, 12
	s_cselect_b32 vcc_hi, s77, s25
	s_cselect_b32 vcc_lo, s76, s24
	s_cselect_b32 s37, s47, s50
	s_cselect_b32 s36, s61, s35
	s_add_i32 m0, s93, 0xc000
	ds_read_b128 v[218:221], v162 offset:6144
	ds_read_b128 v[222:225], v162 offset:7168
	global_load_lds_dwordx4 v140, s[0:1]
	s_add_i32 m0, s93, 0xe000
	s_nop 0
	global_load_lds_dwordx4 v138, s[0:1]
	s_waitcnt lgkmcnt(8)
	s_barrier
	s_waitcnt lgkmcnt(0)
	s_setprio 1
	s_waitcnt lgkmcnt(0)
	v_mfma_f32_16x16x32_bf16 v[126:129], v[164:167], v[194:197], 0
	v_mfma_f32_16x16x32_bf16 v[126:129], v[182:185], v[198:201], v[126:129]
	v_mfma_f32_16x16x32_bf16 v[122:125], v[186:189], v[194:197], 0
	v_mfma_f32_16x16x32_bf16 v[122:125], v[190:193], v[198:201], v[122:125]
	v_mfma_f32_16x16x32_bf16 v[118:121], v[164:167], v[202:205], 0
	v_mfma_f32_16x16x32_bf16 v[118:121], v[182:185], v[206:209], v[118:121]
	v_mfma_f32_16x16x32_bf16 v[110:113], v[186:189], v[202:205], 0
	v_mfma_f32_16x16x32_bf16 v[110:113], v[190:193], v[206:209], v[110:113]
	v_mfma_f32_16x16x32_bf16 v[102:105], v[164:167], v[210:213], 0
	v_mfma_f32_16x16x32_bf16 v[102:105], v[182:185], v[214:217], v[102:105]
	v_mfma_f32_16x16x32_bf16 v[94:97], v[186:189], v[210:213], 0
	v_mfma_f32_16x16x32_bf16 v[94:97], v[190:193], v[214:217], v[94:97]
	v_mfma_f32_16x16x32_bf16 v[86:89], v[164:167], v[218:221], 0
	v_mfma_f32_16x16x32_bf16 v[86:89], v[182:185], v[222:225], v[86:89]
	v_mfma_f32_16x16x32_bf16 v[78:81], v[186:189], v[218:221], 0
	s_barrier
	v_mfma_f32_16x16x32_bf16 v[78:81], v[190:193], v[222:225], v[78:81]
	s_setprio 0
	s_add_i32 s51, 0, 0x14000
	s_add_i32 s24, s39, s86
	ds_read_b128 v[226:229], v249 offset:16384
	ds_read_b128 v[230:233], v249 offset:17408
	ds_read_b128 v[234:237], v249 offset:18432
	ds_read_b128 v[238:241], v249 offset:19456
	s_mov_b32 m0, s24
	global_load_lds_dwordx4 v134, s[36:37]
	s_add_i32 m0, s24, 0x2000
	s_nop 0
	global_load_lds_dwordx4 v130, s[36:37]
	s_barrier
	s_waitcnt lgkmcnt(0)
	s_setprio 1
	s_waitcnt lgkmcnt(0)
	v_mfma_f32_16x16x32_bf16 v[114:117], v[226:229], v[194:197], 0
	v_mfma_f32_16x16x32_bf16 v[114:117], v[230:233], v[198:201], v[114:117]
	v_mfma_f32_16x16x32_bf16 v[106:109], v[234:237], v[194:197], 0
	v_mfma_f32_16x16x32_bf16 v[106:109], v[238:241], v[198:201], v[106:109]
	v_mfma_f32_16x16x32_bf16 v[98:101], v[226:229], v[202:205], 0
	v_mfma_f32_16x16x32_bf16 v[98:101], v[230:233], v[206:209], v[98:101]
	v_mfma_f32_16x16x32_bf16 v[90:93], v[234:237], v[202:205], 0
	v_mfma_f32_16x16x32_bf16 v[90:93], v[238:241], v[206:209], v[90:93]
	v_mfma_f32_16x16x32_bf16 v[82:85], v[226:229], v[210:213], 0
	v_mfma_f32_16x16x32_bf16 v[82:85], v[230:233], v[214:217], v[82:85]
	v_mfma_f32_16x16x32_bf16 v[74:77], v[234:237], v[210:213], 0
	v_mfma_f32_16x16x32_bf16 v[74:77], v[238:241], v[214:217], v[74:77]
	v_mfma_f32_16x16x32_bf16 v[70:73], v[226:229], v[218:221], 0
	v_mfma_f32_16x16x32_bf16 v[70:73], v[230:233], v[222:225], v[70:73]
	v_mfma_f32_16x16x32_bf16 v[66:69], v[234:237], v[218:221], 0
	s_barrier
	v_mfma_f32_16x16x32_bf16 v[66:69], v[238:241], v[222:225], v[66:69]
	s_setprio 0
	s_mov_b32 m0, s93
	ds_read_b128 v[194:197], v162 offset:16384
	ds_read_b128 v[198:201], v162 offset:17408
	ds_read_b128 v[202:205], v162 offset:18432
	ds_read_b128 v[206:209], v162 offset:19456
	ds_read_b128 v[210:213], v162 offset:20480
	ds_read_b128 v[214:217], v162 offset:21504
	ds_read_b128 v[218:221], v162 offset:22528
	ds_read_b128 v[222:225], v162 offset:23552
	global_load_lds_dwordx4 v136, vcc
	s_mov_b32 m0, s94
	s_nop 0
	global_load_lds_dwordx4 v132, vcc
	s_waitcnt vmcnt(8)
	s_barrier
	s_waitcnt lgkmcnt(0)
	s_setprio 1
	s_waitcnt lgkmcnt(0)
	v_mfma_f32_16x16x32_bf16 v[62:65], v[164:167], v[194:197], 0
	v_mfma_f32_16x16x32_bf16 v[62:65], v[182:185], v[198:201], v[62:65]
	v_mfma_f32_16x16x32_bf16 v[58:61], v[186:189], v[194:197], 0
	v_mfma_f32_16x16x32_bf16 v[58:61], v[190:193], v[198:201], v[58:61]
	v_mfma_f32_16x16x32_bf16 v[54:57], v[164:167], v[202:205], 0
	v_mfma_f32_16x16x32_bf16 v[54:57], v[182:185], v[206:209], v[54:57]
	v_mfma_f32_16x16x32_bf16 v[46:49], v[186:189], v[202:205], 0
	v_mfma_f32_16x16x32_bf16 v[46:49], v[190:193], v[206:209], v[46:49]
	v_mfma_f32_16x16x32_bf16 v[38:41], v[164:167], v[210:213], 0
	v_mfma_f32_16x16x32_bf16 v[38:41], v[182:185], v[214:217], v[38:41]
	v_mfma_f32_16x16x32_bf16 v[30:33], v[186:189], v[210:213], 0
	v_mfma_f32_16x16x32_bf16 v[30:33], v[190:193], v[214:217], v[30:33]
	v_mfma_f32_16x16x32_bf16 v[22:25], v[164:167], v[218:221], 0
	v_mfma_f32_16x16x32_bf16 v[22:25], v[182:185], v[222:225], v[22:25]
	v_mfma_f32_16x16x32_bf16 v[14:17], v[186:189], v[218:221], 0
	s_barrier
; #define PG8_STAGE(bufoff, gbase, voff) do { _Pragma("unroll") for (int _i = 0; _i < 2; ++_i) \
;         __builtin_amdgcn_global_load_lds((const unsigned*)((const char*)(gbase) + (voff)[_i]), (LAS unsigned*)(lds + (bufoff) + ldsw + _i * 8192), 16, 0, 0); } while (0)
; #define PG8_LDA(dst, b, h) do { _Pragma("unroll") for (int m = 0; m < 4; ++m) _Pragma("unroll") for (int k = 0; k < 2; ++k) dst[m][k] = *(const LAS bf16x8*)(lds + PG8_SA(b, h) + aoff + m * 2048 + k * 1024); } while (0)
; #define PG8_LDB(dst, b, h) do { _Pragma("unroll") for (int n = 0; n < 2; ++n) _Pragma("unroll") for (int k = 0; k < 2; ++k) dst[n][k] = *(const LAS bf16x8*)(lds + PG8_SB(b, h) + boff + n * 2048 + k * 1024); } while (0)
; #define PG8_MMA(ai, bj, At, Bt) do { __builtin_amdgcn_s_setprio(1); _Pragma("unroll") for (int m = 0; m < 4; ++m) _Pragma("unroll") for (int n = 0; n < 2; ++n) _Pragma("unroll") for (int k = 0; k < 2; ++k) \
;         acc[ai][bj][m][n] = __builtin_amdgcn_mfma_f32_16x16x32_bf16(Bt[n][k], At[m][k], acc[ai][bj][m][n], 0, 0, 0); __builtin_amdgcn_s_setprio(0); } while (0)
; #define PG8_WAIT_V(n) asm volatile("s_waitcnt vmcnt(" #n ")" ::: "memory")
; #define PG8_WAIT_L(n) asm volatile("s_waitcnt lgkmcnt(" #n ")" ::: "memory")
; #define PG8_BAR __builtin_amdgcn_s_barrier()
; #define PG8_SCHED __builtin_amdgcn_sched_barrier(0)
; template <class Epi, class Sched>
; __device__ __forceinline__ void gemm_phase(LAS unsigned char* lds, const Gemm g, const Sched& S, const Epi& E) {
;     ...
;             PG8_WAIT_V(6); PG8_BAR; PG8_MMA(1, 1, At, B1); PG8_BAR;
;             PG8_LDB(B0, 1, 0); PG8_SCHED; PG8_LDA(At, 1, 0); PG8_STAGE(PG8_SA(0, 1), a2 + hstep, voffA);
;             PG8_WAIT_L(8); PG8_BAR; PG8_WAIT_L(0); PG8_MMA(0, 0, At, B0); PG8_BAR; PG8_SCHED;
;             PG8_LDB(B1, 1, 1); PG8_STAGE(PG8_SB(1, 0), b3, voffB);
;             PG8_BAR; PG8_WAIT_L(0); PG8_MMA(0, 1, At, B1); PG8_BAR;
;             PG8_LDA(At, 1, 1); PG8_STAGE(PG8_SA(1, 0), a3, voffA);
;             PG8_BAR; PG8_WAIT_L(0); PG8_MMA(1, 0, At, B0); PG8_BAR; PG8_SCHED;
	v_mfma_f32_16x16x32_bf16 v[14:17], v[190:193], v[222:225], v[14:17]
	s_setprio 0
	s_add_u32 s24, s36, 0x40000
	s_addc_u32 s25, s37, 0
	s_add_i32 s39, s51, s86
	s_mov_b32 m0, s39
	s_nop 0
	global_load_lds_dwordx4 v134, s[24:25]
	s_add_i32 m0, s39, 0x2000
	s_nop 0
	global_load_lds_dwordx4 v130, s[24:25]
	s_waitcnt vmcnt(6)
	s_barrier
	s_setprio 1
	v_mfma_f32_16x16x32_bf16 v[50:53], v[226:229], v[194:197], 0
	ds_read_b128 v[164:167], v249 offset:32768
	ds_read_b128 v[182:185], v249 offset:33792
	v_mfma_f32_16x16x32_bf16 v[50:53], v[230:233], v[198:201], v[50:53]
	ds_read_b128 v[186:189], v249 offset:34816
	ds_read_b128 v[190:193], v249 offset:35840
	v_mfma_f32_16x16x32_bf16 v[42:45], v[234:237], v[194:197], 0
	ds_read_b128 v[194:197], v162 offset:32768
	v_mfma_f32_16x16x32_bf16 v[42:45], v[238:241], v[198:201], v[42:45]
	ds_read_b128 v[198:201], v162 offset:33792
	v_mfma_f32_16x16x32_bf16 v[34:37], v[226:229], v[202:205], 0
	v_mfma_f32_16x16x32_bf16 v[34:37], v[230:233], v[206:209], v[34:37]
	v_mfma_f32_16x16x32_bf16 v[26:29], v[234:237], v[202:205], 0
	ds_read_b128 v[202:205], v162 offset:34816
	v_mfma_f32_16x16x32_bf16 v[26:29], v[238:241], v[206:209], v[26:29]
	ds_read_b128 v[206:209], v162 offset:35840
	v_mfma_f32_16x16x32_bf16 v[18:21], v[226:229], v[210:213], 0
	v_mfma_f32_16x16x32_bf16 v[18:21], v[230:233], v[214:217], v[18:21]
	v_mfma_f32_16x16x32_bf16 v[10:13], v[234:237], v[210:213], 0
	ds_read_b128 v[210:213], v162 offset:36864
	v_mfma_f32_16x16x32_bf16 v[10:13], v[238:241], v[214:217], v[10:13]
	ds_read_b128 v[214:217], v162 offset:37888
	v_mfma_f32_16x16x32_bf16 v[6:9], v[226:229], v[218:221], 0
	v_mfma_f32_16x16x32_bf16 v[6:9], v[230:233], v[222:225], v[6:9]
	v_mfma_f32_16x16x32_bf16 v[2:5], v[234:237], v[218:221], 0
	s_barrier
	v_mfma_f32_16x16x32_bf16 v[2:5], v[238:241], v[222:225], v[2:5]
	s_setprio 0
	s_add_i32 s39, 0, 0x18000
	s_add_u32 s24, vcc_lo, 0x40000
	s_addc_u32 s25, vcc_hi, 0
	s_mov_b32 m0, s95
	ds_read_b128 v[218:221], v162 offset:38912
	ds_read_b128 v[222:225], v162 offset:39936
	global_load_lds_dwordx4 v136, s[24:25]
	s_mov_b32 m0, s96
	s_nop 0
	global_load_lds_dwordx4 v132, s[24:25]
	s_waitcnt lgkmcnt(8)
	s_barrier
	s_waitcnt lgkmcnt(0)
	s_setprio 1
	s_waitcnt lgkmcnt(0)
	v_mfma_f32_16x16x32_bf16 v[126:129], v[164:167], v[194:197], v[126:129]
	v_mfma_f32_16x16x32_bf16 v[126:129], v[182:185], v[198:201], v[126:129]
	v_mfma_f32_16x16x32_bf16 v[122:125], v[186:189], v[194:197], v[122:125]
	v_mfma_f32_16x16x32_bf16 v[122:125], v[190:193], v[198:201], v[122:125]
	v_mfma_f32_16x16x32_bf16 v[118:121], v[164:167], v[202:205], v[118:121]
	v_mfma_f32_16x16x32_bf16 v[118:121], v[182:185], v[206:209], v[118:121]
	v_mfma_f32_16x16x32_bf16 v[110:113], v[186:189], v[202:205], v[110:113]
	v_mfma_f32_16x16x32_bf16 v[110:113], v[190:193], v[206:209], v[110:113]
	v_mfma_f32_16x16x32_bf16 v[102:105], v[164:167], v[210:213], v[102:105]
	v_mfma_f32_16x16x32_bf16 v[102:105], v[182:185], v[214:217], v[102:105]
	v_mfma_f32_16x16x32_bf16 v[94:97], v[186:189], v[210:213], v[94:97]
	v_mfma_f32_16x16x32_bf16 v[94:97], v[190:193], v[214:217], v[94:97]
	v_mfma_f32_16x16x32_bf16 v[86:89], v[164:167], v[218:221], v[86:89]
	v_mfma_f32_16x16x32_bf16 v[86:89], v[182:185], v[222:225], v[86:89]
	v_mfma_f32_16x16x32_bf16 v[78:81], v[186:189], v[218:221], v[78:81]
	s_barrier
	v_mfma_f32_16x16x32_bf16 v[78:81], v[190:193], v[222:225], v[78:81]
	s_setprio 0
	s_add_i32 s51, 0, 0x1c000
	s_add_i32 s24, s39, s86
	s_add_i32 m0, s24, 0xffffff80
	ds_read_b128 v[226:229], v249 offset:49152
	ds_read_b128 v[230:233], v249 offset:50176
	ds_read_b128 v[234:237], v249 offset:51200
	ds_read_b128 v[238:241], v249 offset:52224
	global_load_lds_dwordx4 v134, s[36:37] offset:128
	s_add_i32 m0, s24, 0x1f80
	s_nop 0
	global_load_lds_dwordx4 v130, s[36:37] offset:128
	s_barrier
; #define PG8_STAGE(bufoff, gbase, voff) do { _Pragma("unroll") for (int _i = 0; _i < 2; ++_i) \
;         __builtin_amdgcn_global_load_lds((const unsigned*)((const char*)(gbase) + (voff)[_i]), (LAS unsigned*)(lds + (bufoff) + ldsw + _i * 8192), 16, 0, 0); } while (0)
; #define PG8_LDA(dst, b, h) do { _Pragma("unroll") for (int m = 0; m < 4; ++m) _Pragma("unroll") for (int k = 0; k < 2; ++k) dst[m][k] = *(const LAS bf16x8*)(lds + PG8_SA(b, h) + aoff + m * 2048 + k * 1024); } while (0)
; #define PG8_LDB(dst, b, h) do { _Pragma("unroll") for (int n = 0; n < 2; ++n) _Pragma("unroll") for (int k = 0; k < 2; ++k) dst[n][k] = *(const LAS bf16x8*)(lds + PG8_SB(b, h) + boff + n * 2048 + k * 1024); } while (0)
; #define PG8_MMA(ai, bj, At, Bt) do { __builtin_amdgcn_s_setprio(1); _Pragma("unroll") for (int m = 0; m < 4; ++m) _Pragma("unroll") for (int n = 0; n < 2; ++n) _Pragma("unroll") for (int k = 0; k < 2; ++k) \
;         acc[ai][bj][m][n] = __builtin_amdgcn_mfma_f32_16x16x32_bf16(Bt[n][k], At[m][k], acc[ai][bj][m][n], 0, 0, 0); __builtin_amdgcn_s_setprio(0); } while (0)
; #define PG8_WAIT_V(n) asm volatile("s_waitcnt vmcnt(" #n ")" ::: "memory")
; #define PG8_WAIT_L(n) asm volatile("s_waitcnt lgkmcnt(" #n ")" ::: "memory")
; #define PG8_BAR __builtin_amdgcn_s_barrier()
; #define PG8_SCHED __builtin_amdgcn_sched_barrier(0)
; template <class Epi, class Sched>
; __device__ __forceinline__ void gemm_phase(LAS unsigned char* lds, const Gemm g, const Sched& S, const Epi& E) {
;     ...
;             PG8_WAIT_L(8); PG8_BAR; PG8_WAIT_L(0); PG8_MMA(0, 0, At, B0); PG8_BAR; PG8_SCHED;
;             PG8_LDB(B1, 1, 1); PG8_STAGE(PG8_SB(1, 0), b3, voffB);
;             PG8_BAR; PG8_WAIT_L(0); PG8_MMA(0, 1, At, B1); PG8_BAR;
;             PG8_LDA(At, 1, 1); PG8_STAGE(PG8_SA(1, 0), a3, voffA);
;             PG8_BAR; PG8_WAIT_L(0); PG8_MMA(1, 0, At, B0); PG8_BAR; PG8_SCHED;
;             PG8_STAGE(PG8_SB(1, 1), b3 + hstep, voffB);
;             PG8_WAIT_V(6); PG8_BAR; PG8_MMA(1, 1, At, B1); PG8_BAR;
;         }
	s_waitcnt lgkmcnt(0)
	s_setprio 1
	s_waitcnt lgkmcnt(0)
	v_mfma_f32_16x16x32_bf16 v[114:117], v[226:229], v[194:197], v[114:117]
	v_mfma_f32_16x16x32_bf16 v[114:117], v[230:233], v[198:201], v[114:117]
	v_mfma_f32_16x16x32_bf16 v[106:109], v[234:237], v[194:197], v[106:109]
	v_mfma_f32_16x16x32_bf16 v[106:109], v[238:241], v[198:201], v[106:109]
	v_mfma_f32_16x16x32_bf16 v[98:101], v[226:229], v[202:205], v[98:101]
	v_mfma_f32_16x16x32_bf16 v[98:101], v[230:233], v[206:209], v[98:101]
	v_mfma_f32_16x16x32_bf16 v[90:93], v[234:237], v[202:205], v[90:93]
	v_mfma_f32_16x16x32_bf16 v[90:93], v[238:241], v[206:209], v[90:93]
	v_mfma_f32_16x16x32_bf16 v[82:85], v[226:229], v[210:213], v[82:85]
	v_mfma_f32_16x16x32_bf16 v[82:85], v[230:233], v[214:217], v[82:85]
	v_mfma_f32_16x16x32_bf16 v[74:77], v[234:237], v[210:213], v[74:77]
	v_mfma_f32_16x16x32_bf16 v[74:77], v[238:241], v[214:217], v[74:77]
	v_mfma_f32_16x16x32_bf16 v[70:73], v[226:229], v[218:221], v[70:73]
	v_mfma_f32_16x16x32_bf16 v[70:73], v[230:233], v[222:225], v[70:73]
	v_mfma_f32_16x16x32_bf16 v[66:69], v[234:237], v[218:221], v[66:69]
	s_barrier
	v_mfma_f32_16x16x32_bf16 v[66:69], v[238:241], v[222:225], v[66:69]
	s_setprio 0
	s_add_i32 m0, s97, 0xffffff80
	ds_read_b128 v[194:197], v162 offset:49152
	ds_read_b128 v[198:201], v162 offset:50176
	ds_read_b128 v[202:205], v162 offset:51200
	ds_read_b128 v[206:209], v162 offset:52224
	ds_read_b128 v[210:213], v162 offset:53248
	ds_read_b128 v[214:217], v162 offset:54272
	ds_read_b128 v[218:221], v162 offset:55296
	ds_read_b128 v[222:225], v162 offset:56320
	global_load_lds_dwordx4 v136, vcc offset:128
	s_add_i32 m0, s98, 0xffffff80
	s_nop 0
	global_load_lds_dwordx4 v132, vcc offset:128
	s_waitcnt vmcnt(8)
	s_barrier
	s_waitcnt lgkmcnt(0)
	s_setprio 1
	s_waitcnt lgkmcnt(0)
	v_mfma_f32_16x16x32_bf16 v[62:65], v[164:167], v[194:197], v[62:65]
	v_mfma_f32_16x16x32_bf16 v[62:65], v[182:185], v[198:201], v[62:65]
	v_mfma_f32_16x16x32_bf16 v[58:61], v[186:189], v[194:197], v[58:61]
	v_mfma_f32_16x16x32_bf16 v[58:61], v[190:193], v[198:201], v[58:61]
	v_mfma_f32_16x16x32_bf16 v[54:57], v[164:167], v[202:205], v[54:57]
	v_mfma_f32_16x16x32_bf16 v[54:57], v[182:185], v[206:209], v[54:57]
	v_mfma_f32_16x16x32_bf16 v[46:49], v[186:189], v[202:205], v[46:49]
	v_mfma_f32_16x16x32_bf16 v[46:49], v[190:193], v[206:209], v[46:49]
	v_mfma_f32_16x16x32_bf16 v[38:41], v[164:167], v[210:213], v[38:41]
	v_mfma_f32_16x16x32_bf16 v[38:41], v[182:185], v[214:217], v[38:41]
	v_mfma_f32_16x16x32_bf16 v[30:33], v[186:189], v[210:213], v[30:33]
	v_mfma_f32_16x16x32_bf16 v[30:33], v[190:193], v[214:217], v[30:33]
	v_mfma_f32_16x16x32_bf16 v[22:25], v[164:167], v[218:221], v[22:25]
	v_mfma_f32_16x16x32_bf16 v[22:25], v[182:185], v[222:225], v[22:25]
	v_mfma_f32_16x16x32_bf16 v[14:17], v[186:189], v[218:221], v[14:17]
	s_barrier
	v_mfma_f32_16x16x32_bf16 v[14:17], v[190:193], v[222:225], v[14:17]
	s_setprio 0
	s_add_u32 s24, s36, 0x40080
	s_addc_u32 s25, s37, 0
	s_add_i32 s36, s51, s86
	s_mov_b32 m0, s36
	s_nop 0
	global_load_lds_dwordx4 v134, s[24:25]
	s_add_i32 m0, s36, 0x2000
	s_nop 0
	global_load_lds_dwordx4 v130, s[24:25]
	s_waitcnt vmcnt(6)
	s_barrier
	s_setprio 1
	v_mfma_f32_16x16x32_bf16 v[50:53], v[226:229], v[194:197], v[50:53]
	ds_read_b128 v[164:167], v249
	ds_read_b128 v[182:185], v249 offset:1024
	v_mfma_f32_16x16x32_bf16 v[50:53], v[230:233], v[198:201], v[50:53]
	ds_read_b128 v[186:189], v249 offset:2048
	ds_read_b128 v[190:193], v249 offset:3072
	v_mfma_f32_16x16x32_bf16 v[42:45], v[234:237], v[194:197], v[42:45]
	ds_read_b128 v[194:197], v162
	v_mfma_f32_16x16x32_bf16 v[42:45], v[238:241], v[198:201], v[42:45]
	ds_read_b128 v[198:201], v162 offset:1024
	v_mfma_f32_16x16x32_bf16 v[34:37], v[226:229], v[202:205], v[34:37]
	v_mfma_f32_16x16x32_bf16 v[34:37], v[230:233], v[206:209], v[34:37]
	v_mfma_f32_16x16x32_bf16 v[26:29], v[234:237], v[202:205], v[26:29]
	ds_read_b128 v[202:205], v162 offset:2048
	v_mfma_f32_16x16x32_bf16 v[26:29], v[238:241], v[206:209], v[26:29]
	ds_read_b128 v[206:209], v162 offset:3072
	v_mfma_f32_16x16x32_bf16 v[18:21], v[226:229], v[210:213], v[18:21]
	v_mfma_f32_16x16x32_bf16 v[18:21], v[230:233], v[214:217], v[18:21]
	v_mfma_f32_16x16x32_bf16 v[10:13], v[234:237], v[210:213], v[10:13]
	ds_read_b128 v[210:213], v162 offset:4096
	v_mfma_f32_16x16x32_bf16 v[10:13], v[238:241], v[214:217], v[10:13]
	ds_read_b128 v[214:217], v162 offset:5120
	v_mfma_f32_16x16x32_bf16 v[6:9], v[226:229], v[218:221], v[6:9]
	v_mfma_f32_16x16x32_bf16 v[6:9], v[230:233], v[222:225], v[6:9]
	v_mfma_f32_16x16x32_bf16 v[2:5], v[234:237], v[218:221], v[2:5]
	s_barrier
	v_mfma_f32_16x16x32_bf16 v[2:5], v[238:241], v[222:225], v[2:5]
	s_setprio 0
	s_add_i32 s38, s38, 2
	s_add_u32 s35, s35, 0x100
	s_addc_u32 s50, s50, 0
	s_add_u32 s0, s0, 0x100
	s_addc_u32 s1, s1, 0
	s_cmp_gt_u32 s38, 13

; #define PG8_STAGE(bufoff, gbase, voff) do { _Pragma("unroll") for (int _i = 0; _i < 2; ++_i) \
;         __builtin_amdgcn_global_load_lds((const unsigned*)((const char*)(gbase) + (voff)[_i]), (LAS unsigned*)(lds + (bufoff) + ldsw + _i * 8192), 16, 0, 0); } while (0)
; #define PG8_LDA(dst, b, h) do { _Pragma("unroll") for (int m = 0; m < 4; ++m) _Pragma("unroll") for (int k = 0; k < 2; ++k) dst[m][k] = *(const LAS bf16x8*)(lds + PG8_SA(b, h) + aoff + m * 2048 + k * 1024); } while (0)
; #define PG8_LDB(dst, b, h) do { _Pragma("unroll") for (int n = 0; n < 2; ++n) _Pragma("unroll") for (int k = 0; k < 2; ++k) dst[n][k] = *(const LAS bf16x8*)(lds + PG8_SB(b, h) + boff + n * 2048 + k * 1024); } while (0)
; #define PG8_WAIT_V(n) asm volatile("s_waitcnt vmcnt(" #n ")" ::: "memory")
; #define PG8_WAIT_L(n) asm volatile("s_waitcnt lgkmcnt(" #n ")" ::: "memory")
; #define PG8_BAR __builtin_amdgcn_s_barrier()
; #define PG8_SCHED __builtin_amdgcn_sched_barrier(0)
; template <class Epi, class Sched>
; __device__ __forceinline__ void gemm_phase(LAS unsigned char* lds, const Gemm g, const Sched& S, const Epi& E) {
;     ...
;         const bool has_next = S.next(ui + 1, nxt);
;         const char* nA = has_next ? PG8_APANEL(nxt.pm) : cA; const char* nB = has_next ? (const char*)g.Bt + (size_t)nxt.pn * tstep : cB;
;         for (int t = 0; t < nt; t += 2) {
;             const bool last = (t == nt - 2);
;             const char* a1 = cA + (size_t)(t + 1) * kstep;
;             const char* a2 = last ? nA : cA + (size_t)(t + 2) * kstep; const char* b2 = last ? nB : cB + (size_t)(t + 2) * kstep;
;             const char* a3 = a2 + kstep; const char* b3 = b2 + kstep;
;             PG8_LDB(B0, 0, 0); PG8_SCHED; PG8_LDA(At, 0, 0); PG8_STAGE(PG8_SA(1, 1), a1 + hstep, voffA);
;             PG8_WAIT_L(8); PG8_BAR; PG8_WAIT_L(0); PG8_MMA(0, 0, At, B0); PG8_BAR; PG8_SCHED;
;             PG8_LDB(B1, 0, 1); PG8_STAGE(PG8_SB(0, 0), b2, voffB);
;             PG8_BAR; PG8_WAIT_L(0); PG8_MMA(0, 1, At, B1); PG8_BAR;
;             PG8_LDA(At, 0, 1); PG8_STAGE(PG8_SA(0, 0), a2, voffA);
;             PG8_BAR; PG8_WAIT_L(0); PG8_MMA(1, 0, At, B0); PG8_BAR; PG8_SCHED;
;             PG8_STAGE(PG8_SB(0, 1), b2 + hstep, voffB);
;             PG8_WAIT_V(6); PG8_BAR; PG8_MMA(1, 1, At, B1); PG8_BAR;
.LBB0_556:
	s_ashr_i32 s45, s44, 31
	s_lshl_b64 s[24:25], s[44:45], 19
	s_add_u32 s60, s86, s24
	s_addc_u32 s61, s93, s25
	s_and_b64 s[0:1], s[0:1], exec
	s_cselect_b32 s45, s61, s49
	s_cselect_b32 s47, s60, s48
	s_add_u32 s35, s48, 0x100
	s_addc_u32 s50, s49, 0
	s_add_u32 s0, s38, 0x40080
	s_addc_u32 s1, s39, 0
	s_mov_b32 s38, -2
	v_add_u32_e32 v249, 0x10000, v164
	ds_read_b128 v[142:145], v249
	ds_read_b128 v[182:185], v249 offset:1024
	ds_read_b128 v[186:189], v249 offset:2048
	ds_read_b128 v[190:193], v249 offset:3072
	ds_read_b128 v[194:197], v166
	ds_read_b128 v[198:201], v166 offset:1024
	ds_read_b128 v[202:205], v166 offset:2048
	ds_read_b128 v[206:209], v166 offset:3072
	ds_read_b128 v[210:213], v166 offset:4096
	ds_read_b128 v[214:217], v166 offset:5120
	s_add_u32 s24, s0, 0xfffc0080
	s_addc_u32 s25, s1, -1
	s_add_i32 s39, 0, 0x10000
	s_cmp_eq_u32 s38, 12
	s_cselect_b32 vcc_hi, s77, s25
	s_cselect_b32 vcc_lo, s76, s24
	s_cselect_b32 s49, s45, s50
	s_cselect_b32 s48, s47, s35
	s_add_i32 m0, s95, 0xc000
	ds_read_b128 v[218:221], v166 offset:6144
	ds_read_b128 v[222:225], v166 offset:7168
	global_load_lds_dwordx4 v140, s[0:1]
	s_add_i32 m0, s95, 0xe000
	s_nop 0
	global_load_lds_dwordx4 v138, s[0:1]
	s_waitcnt lgkmcnt(8)
	s_barrier
	s_waitcnt lgkmcnt(0)
	s_setprio 1
	s_waitcnt lgkmcnt(0)
	v_mfma_f32_16x16x32_bf16 v[126:129], v[142:145], v[194:197], 0
	v_mfma_f32_16x16x32_bf16 v[126:129], v[182:185], v[198:201], v[126:129]
	v_mfma_f32_16x16x32_bf16 v[122:125], v[186:189], v[194:197], 0
	v_mfma_f32_16x16x32_bf16 v[122:125], v[190:193], v[198:201], v[122:125]
	v_mfma_f32_16x16x32_bf16 v[110:113], v[142:145], v[202:205], 0
	v_mfma_f32_16x16x32_bf16 v[110:113], v[182:185], v[206:209], v[110:113]
	v_mfma_f32_16x16x32_bf16 v[106:109], v[186:189], v[202:205], 0
	v_mfma_f32_16x16x32_bf16 v[106:109], v[190:193], v[206:209], v[106:109]
	v_mfma_f32_16x16x32_bf16 v[94:97], v[142:145], v[210:213], 0
	v_mfma_f32_16x16x32_bf16 v[94:97], v[182:185], v[214:217], v[94:97]
	v_mfma_f32_16x16x32_bf16 v[90:93], v[186:189], v[210:213], 0
	v_mfma_f32_16x16x32_bf16 v[90:93], v[190:193], v[214:217], v[90:93]
	v_mfma_f32_16x16x32_bf16 v[78:81], v[142:145], v[218:221], 0
	v_mfma_f32_16x16x32_bf16 v[78:81], v[182:185], v[222:225], v[78:81]
	v_mfma_f32_16x16x32_bf16 v[74:77], v[186:189], v[218:221], 0
	s_barrier
	v_mfma_f32_16x16x32_bf16 v[74:77], v[190:193], v[222:225], v[74:77]
	s_setprio 0
	s_add_i32 s51, 0, 0x14000
	s_add_i32 s24, s39, s94
	ds_read_b128 v[226:229], v249 offset:16384
	ds_read_b128 v[230:233], v249 offset:17408
	ds_read_b128 v[234:237], v249 offset:18432
	ds_read_b128 v[238:241], v249 offset:19456
	s_mov_b32 m0, s24
	global_load_lds_dwordx4 v134, s[48:49]
	s_add_i32 m0, s24, 0x2000
	s_nop 0
	global_load_lds_dwordx4 v130, s[48:49]
	s_barrier
	s_waitcnt lgkmcnt(0)
	s_setprio 1
	s_waitcnt lgkmcnt(0)
	v_mfma_f32_16x16x32_bf16 v[118:121], v[226:229], v[194:197], 0
	v_mfma_f32_16x16x32_bf16 v[118:121], v[230:233], v[198:201], v[118:121]
	v_mfma_f32_16x16x32_bf16 v[114:117], v[234:237], v[194:197], 0
	v_mfma_f32_16x16x32_bf16 v[114:117], v[238:241], v[198:201], v[114:117]
	v_mfma_f32_16x16x32_bf16 v[102:105], v[226:229], v[202:205], 0
	v_mfma_f32_16x16x32_bf16 v[102:105], v[230:233], v[206:209], v[102:105]
	v_mfma_f32_16x16x32_bf16 v[98:101], v[234:237], v[202:205], 0
	v_mfma_f32_16x16x32_bf16 v[98:101], v[238:241], v[206:209], v[98:101]
	v_mfma_f32_16x16x32_bf16 v[86:89], v[226:229], v[210:213], 0
	v_mfma_f32_16x16x32_bf16 v[86:89], v[230:233], v[214:217], v[86:89]
	v_mfma_f32_16x16x32_bf16 v[82:85], v[234:237], v[210:213], 0
	v_mfma_f32_16x16x32_bf16 v[82:85], v[238:241], v[214:217], v[82:85]
	v_mfma_f32_16x16x32_bf16 v[70:73], v[226:229], v[218:221], 0
	v_mfma_f32_16x16x32_bf16 v[70:73], v[230:233], v[222:225], v[70:73]
	v_mfma_f32_16x16x32_bf16 v[66:69], v[234:237], v[218:221], 0
	s_barrier
	v_mfma_f32_16x16x32_bf16 v[66:69], v[238:241], v[222:225], v[66:69]
	s_setprio 0
	s_mov_b32 m0, s95
	ds_read_b128 v[194:197], v166 offset:16384
	ds_read_b128 v[198:201], v166 offset:17408
	ds_read_b128 v[202:205], v166 offset:18432
	ds_read_b128 v[206:209], v166 offset:19456
	ds_read_b128 v[210:213], v166 offset:20480
	ds_read_b128 v[214:217], v166 offset:21504
	ds_read_b128 v[218:221], v166 offset:22528
	ds_read_b128 v[222:225], v166 offset:23552
	global_load_lds_dwordx4 v136, vcc
	s_mov_b32 m0, s96
	s_nop 0
	global_load_lds_dwordx4 v132, vcc
	s_waitcnt vmcnt(8)
	s_barrier
	s_waitcnt lgkmcnt(0)
	s_setprio 1
	s_waitcnt lgkmcnt(0)
	v_mfma_f32_16x16x32_bf16 v[62:65], v[142:145], v[194:197], 0
	v_mfma_f32_16x16x32_bf16 v[62:65], v[182:185], v[198:201], v[62:65]
	v_mfma_f32_16x16x32_bf16 v[58:61], v[186:189], v[194:197], 0
	v_mfma_f32_16x16x32_bf16 v[58:61], v[190:193], v[198:201], v[58:61]
	v_mfma_f32_16x16x32_bf16 v[46:49], v[142:145], v[202:205], 0
	v_mfma_f32_16x16x32_bf16 v[46:49], v[182:185], v[206:209], v[46:49]
	v_mfma_f32_16x16x32_bf16 v[42:45], v[186:189], v[202:205], 0
	v_mfma_f32_16x16x32_bf16 v[42:45], v[190:193], v[206:209], v[42:45]
	v_mfma_f32_16x16x32_bf16 v[30:33], v[142:145], v[210:213], 0
	v_mfma_f32_16x16x32_bf16 v[30:33], v[182:185], v[214:217], v[30:33]
	v_mfma_f32_16x16x32_bf16 v[26:29], v[186:189], v[210:213], 0
	v_mfma_f32_16x16x32_bf16 v[26:29], v[190:193], v[214:217], v[26:29]
	v_mfma_f32_16x16x32_bf16 v[14:17], v[142:145], v[218:221], 0
	v_mfma_f32_16x16x32_bf16 v[14:17], v[182:185], v[222:225], v[14:17]
	v_mfma_f32_16x16x32_bf16 v[10:13], v[186:189], v[218:221], 0
	s_barrier
; #define PG8_STAGE(bufoff, gbase, voff) do { _Pragma("unroll") for (int _i = 0; _i < 2; ++_i) \
;         __builtin_amdgcn_global_load_lds((const unsigned*)((const char*)(gbase) + (voff)[_i]), (LAS unsigned*)(lds + (bufoff) + ldsw + _i * 8192), 16, 0, 0); } while (0)
; #define PG8_LDA(dst, b, h) do { _Pragma("unroll") for (int m = 0; m < 4; ++m) _Pragma("unroll") for (int k = 0; k < 2; ++k) dst[m][k] = *(const LAS bf16x8*)(lds + PG8_SA(b, h) + aoff + m * 2048 + k * 1024); } while (0)
; #define PG8_LDB(dst, b, h) do { _Pragma("unroll") for (int n = 0; n < 2; ++n) _Pragma("unroll") for (int k = 0; k < 2; ++k) dst[n][k] = *(const LAS bf16x8*)(lds + PG8_SB(b, h) + boff + n * 2048 + k * 1024); } while (0)
; #define PG8_MMA(ai, bj, At, Bt) do { __builtin_amdgcn_s_setprio(1); _Pragma("unroll") for (int m = 0; m < 4; ++m) _Pragma("unroll") for (int n = 0; n < 2; ++n) _Pragma("unroll") for (int k = 0; k < 2; ++k) \
;         acc[ai][bj][m][n] = __builtin_amdgcn_mfma_f32_16x16x32_bf16(Bt[n][k], At[m][k], acc[ai][bj][m][n], 0, 0, 0); __builtin_amdgcn_s_setprio(0); } while (0)
; #define PG8_WAIT_V(n) asm volatile("s_waitcnt vmcnt(" #n ")" ::: "memory")
; #define PG8_WAIT_L(n) asm volatile("s_waitcnt lgkmcnt(" #n ")" ::: "memory")
; #define PG8_BAR __builtin_amdgcn_s_barrier()
; #define PG8_SCHED __builtin_amdgcn_sched_barrier(0)
; template <class Epi, class Sched>
; __device__ __forceinline__ void gemm_phase(LAS unsigned char* lds, const Gemm g, const Sched& S, const Epi& E) {
;     ...
;             PG8_WAIT_V(6); PG8_BAR; PG8_MMA(1, 1, At, B1); PG8_BAR;
;             PG8_LDB(B0, 1, 0); PG8_SCHED; PG8_LDA(At, 1, 0); PG8_STAGE(PG8_SA(0, 1), a2 + hstep, voffA);
;             PG8_WAIT_L(8); PG8_BAR; PG8_WAIT_L(0); PG8_MMA(0, 0, At, B0); PG8_BAR; PG8_SCHED;
;             PG8_LDB(B1, 1, 1); PG8_STAGE(PG8_SB(1, 0), b3, voffB);
;             PG8_BAR; PG8_WAIT_L(0); PG8_MMA(0, 1, At, B1); PG8_BAR;
;             PG8_LDA(At, 1, 1); PG8_STAGE(PG8_SA(1, 0), a3, voffA);
;             PG8_BAR; PG8_WAIT_L(0); PG8_MMA(1, 0, At, B0); PG8_BAR; PG8_SCHED;
	v_mfma_f32_16x16x32_bf16 v[10:13], v[190:193], v[222:225], v[10:13]
	s_setprio 0
	s_add_u32 s24, s48, 0x40000
	s_addc_u32 s25, s49, 0
	s_add_i32 s39, s51, s94
	s_mov_b32 m0, s39
	s_nop 0
	global_load_lds_dwordx4 v134, s[24:25]
	s_add_i32 m0, s39, 0x2000
	s_nop 0
	global_load_lds_dwordx4 v130, s[24:25]
	s_waitcnt vmcnt(6)
	s_barrier
	s_setprio 1
	v_mfma_f32_16x16x32_bf16 v[54:57], v[226:229], v[194:197], 0
	ds_read_b128 v[142:145], v249 offset:32768
	ds_read_b128 v[182:185], v249 offset:33792
	v_mfma_f32_16x16x32_bf16 v[54:57], v[230:233], v[198:201], v[54:57]
	ds_read_b128 v[186:189], v249 offset:34816
	ds_read_b128 v[190:193], v249 offset:35840
	v_mfma_f32_16x16x32_bf16 v[50:53], v[234:237], v[194:197], 0
	ds_read_b128 v[194:197], v166 offset:32768
	v_mfma_f32_16x16x32_bf16 v[50:53], v[238:241], v[198:201], v[50:53]
	ds_read_b128 v[198:201], v166 offset:33792
	v_mfma_f32_16x16x32_bf16 v[38:41], v[226:229], v[202:205], 0
	v_mfma_f32_16x16x32_bf16 v[38:41], v[230:233], v[206:209], v[38:41]
	v_mfma_f32_16x16x32_bf16 v[34:37], v[234:237], v[202:205], 0
	ds_read_b128 v[202:205], v166 offset:34816
	v_mfma_f32_16x16x32_bf16 v[34:37], v[238:241], v[206:209], v[34:37]
	ds_read_b128 v[206:209], v166 offset:35840
	v_mfma_f32_16x16x32_bf16 v[22:25], v[226:229], v[210:213], 0
	v_mfma_f32_16x16x32_bf16 v[22:25], v[230:233], v[214:217], v[22:25]
	v_mfma_f32_16x16x32_bf16 v[18:21], v[234:237], v[210:213], 0
	ds_read_b128 v[210:213], v166 offset:36864
	v_mfma_f32_16x16x32_bf16 v[18:21], v[238:241], v[214:217], v[18:21]
	ds_read_b128 v[214:217], v166 offset:37888
	v_mfma_f32_16x16x32_bf16 v[6:9], v[226:229], v[218:221], 0
	v_mfma_f32_16x16x32_bf16 v[6:9], v[230:233], v[222:225], v[6:9]
	v_mfma_f32_16x16x32_bf16 v[2:5], v[234:237], v[218:221], 0
	s_barrier
	v_mfma_f32_16x16x32_bf16 v[2:5], v[238:241], v[222:225], v[2:5]
	s_setprio 0
	s_add_i32 s39, 0, 0x18000
	s_add_u32 s24, vcc_lo, 0x40000
	s_addc_u32 s25, vcc_hi, 0
	s_mov_b32 m0, s97
	ds_read_b128 v[218:221], v166 offset:38912
	ds_read_b128 v[222:225], v166 offset:39936
	global_load_lds_dwordx4 v136, s[24:25]
	s_mov_b32 m0, s98
	s_nop 0
	global_load_lds_dwordx4 v132, s[24:25]
	s_waitcnt lgkmcnt(8)
	s_barrier
	s_waitcnt lgkmcnt(0)
	s_setprio 1
	s_waitcnt lgkmcnt(0)
	v_mfma_f32_16x16x32_bf16 v[126:129], v[142:145], v[194:197], v[126:129]
	v_mfma_f32_16x16x32_bf16 v[126:129], v[182:185], v[198:201], v[126:129]
	v_mfma_f32_16x16x32_bf16 v[122:125], v[186:189], v[194:197], v[122:125]
	v_mfma_f32_16x16x32_bf16 v[122:125], v[190:193], v[198:201], v[122:125]
	v_mfma_f32_16x16x32_bf16 v[110:113], v[142:145], v[202:205], v[110:113]
	v_mfma_f32_16x16x32_bf16 v[110:113], v[182:185], v[206:209], v[110:113]
	v_mfma_f32_16x16x32_bf16 v[106:109], v[186:189], v[202:205], v[106:109]
	v_mfma_f32_16x16x32_bf16 v[106:109], v[190:193], v[206:209], v[106:109]
	v_mfma_f32_16x16x32_bf16 v[94:97], v[142:145], v[210:213], v[94:97]
	v_mfma_f32_16x16x32_bf16 v[94:97], v[182:185], v[214:217], v[94:97]
	v_mfma_f32_16x16x32_bf16 v[90:93], v[186:189], v[210:213], v[90:93]
	v_mfma_f32_16x16x32_bf16 v[90:93], v[190:193], v[214:217], v[90:93]
	v_mfma_f32_16x16x32_bf16 v[78:81], v[142:145], v[218:221], v[78:81]
	v_mfma_f32_16x16x32_bf16 v[78:81], v[182:185], v[222:225], v[78:81]
	v_mfma_f32_16x16x32_bf16 v[74:77], v[186:189], v[218:221], v[74:77]
	s_barrier
	v_mfma_f32_16x16x32_bf16 v[74:77], v[190:193], v[222:225], v[74:77]
	s_setprio 0
	s_add_i32 s51, 0, 0x1c000
	s_add_i32 s24, s39, s94
	s_add_i32 m0, s24, 0xffffff80
	ds_read_b128 v[226:229], v249 offset:49152
	ds_read_b128 v[230:233], v249 offset:50176
	ds_read_b128 v[234:237], v249 offset:51200
	ds_read_b128 v[238:241], v249 offset:52224
	global_load_lds_dwordx4 v134, s[48:49] offset:128
	s_add_i32 m0, s24, 0x1f80
	s_nop 0
	global_load_lds_dwordx4 v130, s[48:49] offset:128
	s_barrier
; #define PG8_STAGE(bufoff, gbase, voff) do { _Pragma("unroll") for (int _i = 0; _i < 2; ++_i) \
;         __builtin_amdgcn_global_load_lds((const unsigned*)((const char*)(gbase) + (voff)[_i]), (LAS unsigned*)(lds + (bufoff) + ldsw + _i * 8192), 16, 0, 0); } while (0)
; #define PG8_LDA(dst, b, h) do { _Pragma("unroll") for (int m = 0; m < 4; ++m) _Pragma("unroll") for (int k = 0; k < 2; ++k) dst[m][k] = *(const LAS bf16x8*)(lds + PG8_SA(b, h) + aoff + m * 2048 + k * 1024); } while (0)
; #define PG8_LDB(dst, b, h) do { _Pragma("unroll") for (int n = 0; n < 2; ++n) _Pragma("unroll") for (int k = 0; k < 2; ++k) dst[n][k] = *(const LAS bf16x8*)(lds + PG8_SB(b, h) + boff + n * 2048 + k * 1024); } while (0)
; #define PG8_MMA(ai, bj, At, Bt) do { __builtin_amdgcn_s_setprio(1); _Pragma("unroll") for (int m = 0; m < 4; ++m) _Pragma("unroll") for (int n = 0; n < 2; ++n) _Pragma("unroll") for (int k = 0; k < 2; ++k) \
;         acc[ai][bj][m][n] = __builtin_amdgcn_mfma_f32_16x16x32_bf16(Bt[n][k], At[m][k], acc[ai][bj][m][n], 0, 0, 0); __builtin_amdgcn_s_setprio(0); } while (0)
; #define PG8_WAIT_V(n) asm volatile("s_waitcnt vmcnt(" #n ")" ::: "memory")
; #define PG8_WAIT_L(n) asm volatile("s_waitcnt lgkmcnt(" #n ")" ::: "memory")
; #define PG8_BAR __builtin_amdgcn_s_barrier()
; #define PG8_SCHED __builtin_amdgcn_sched_barrier(0)
; template <class Epi, class Sched>
; __device__ __forceinline__ void gemm_phase(LAS unsigned char* lds, const Gemm g, const Sched& S, const Epi& E) {
;     ...
;             PG8_WAIT_L(8); PG8_BAR; PG8_WAIT_L(0); PG8_MMA(0, 0, At, B0); PG8_BAR; PG8_SCHED;
;             PG8_LDB(B1, 1, 1); PG8_STAGE(PG8_SB(1, 0), b3, voffB);
;             PG8_BAR; PG8_WAIT_L(0); PG8_MMA(0, 1, At, B1); PG8_BAR;
;             PG8_LDA(At, 1, 1); PG8_STAGE(PG8_SA(1, 0), a3, voffA);
;             PG8_BAR; PG8_WAIT_L(0); PG8_MMA(1, 0, At, B0); PG8_BAR; PG8_SCHED;
;             PG8_STAGE(PG8_SB(1, 1), b3 + hstep, voffB);
;             PG8_WAIT_V(6); PG8_BAR; PG8_MMA(1, 1, At, B1); PG8_BAR;
;         }
	s_waitcnt lgkmcnt(0)
	s_setprio 1
	s_waitcnt lgkmcnt(0)
	v_mfma_f32_16x16x32_bf16 v[118:121], v[226:229], v[194:197], v[118:121]
	v_mfma_f32_16x16x32_bf16 v[118:121], v[230:233], v[198:201], v[118:121]
	v_mfma_f32_16x16x32_bf16 v[114:117], v[234:237], v[194:197], v[114:117]
	v_mfma_f32_16x16x32_bf16 v[114:117], v[238:241], v[198:201], v[114:117]
	v_mfma_f32_16x16x32_bf16 v[102:105], v[226:229], v[202:205], v[102:105]
	v_mfma_f32_16x16x32_bf16 v[102:105], v[230:233], v[206:209], v[102:105]
	v_mfma_f32_16x16x32_bf16 v[98:101], v[234:237], v[202:205], v[98:101]
	v_mfma_f32_16x16x32_bf16 v[98:101], v[238:241], v[206:209], v[98:101]
	v_mfma_f32_16x16x32_bf16 v[86:89], v[226:229], v[210:213], v[86:89]
	v_mfma_f32_16x16x32_bf16 v[86:89], v[230:233], v[214:217], v[86:89]
	v_mfma_f32_16x16x32_bf16 v[82:85], v[234:237], v[210:213], v[82:85]
	v_mfma_f32_16x16x32_bf16 v[82:85], v[238:241], v[214:217], v[82:85]
	v_mfma_f32_16x16x32_bf16 v[70:73], v[226:229], v[218:221], v[70:73]
	v_mfma_f32_16x16x32_bf16 v[70:73], v[230:233], v[222:225], v[70:73]
	v_mfma_f32_16x16x32_bf16 v[66:69], v[234:237], v[218:221], v[66:69]
	s_barrier
	v_mfma_f32_16x16x32_bf16 v[66:69], v[238:241], v[222:225], v[66:69]
	s_setprio 0
	s_add_i32 m0, s99, 0xffffff80
	ds_read_b128 v[194:197], v166 offset:49152
	ds_read_b128 v[198:201], v166 offset:50176
	ds_read_b128 v[202:205], v166 offset:51200
	ds_read_b128 v[206:209], v166 offset:52224
	ds_read_b128 v[210:213], v166 offset:53248
	ds_read_b128 v[214:217], v166 offset:54272
	ds_read_b128 v[218:221], v166 offset:55296
	ds_read_b128 v[222:225], v166 offset:56320
	global_load_lds_dwordx4 v136, vcc offset:128
	s_add_i32 m0, s82, 0xffffff80
	s_nop 0
	global_load_lds_dwordx4 v132, vcc offset:128
	s_waitcnt vmcnt(8)
	s_barrier
	s_waitcnt lgkmcnt(0)
	s_setprio 1
	s_waitcnt lgkmcnt(0)
	v_mfma_f32_16x16x32_bf16 v[62:65], v[142:145], v[194:197], v[62:65]
	v_mfma_f32_16x16x32_bf16 v[62:65], v[182:185], v[198:201], v[62:65]
	v_mfma_f32_16x16x32_bf16 v[58:61], v[186:189], v[194:197], v[58:61]
	v_mfma_f32_16x16x32_bf16 v[58:61], v[190:193], v[198:201], v[58:61]
	v_mfma_f32_16x16x32_bf16 v[46:49], v[142:145], v[202:205], v[46:49]
	v_mfma_f32_16x16x32_bf16 v[46:49], v[182:185], v[206:209], v[46:49]
	v_mfma_f32_16x16x32_bf16 v[42:45], v[186:189], v[202:205], v[42:45]
	v_mfma_f32_16x16x32_bf16 v[42:45], v[190:193], v[206:209], v[42:45]
	v_mfma_f32_16x16x32_bf16 v[30:33], v[142:145], v[210:213], v[30:33]
	v_mfma_f32_16x16x32_bf16 v[30:33], v[182:185], v[214:217], v[30:33]
	v_mfma_f32_16x16x32_bf16 v[26:29], v[186:189], v[210:213], v[26:29]
	v_mfma_f32_16x16x32_bf16 v[26:29], v[190:193], v[214:217], v[26:29]
	v_mfma_f32_16x16x32_bf16 v[14:17], v[142:145], v[218:221], v[14:17]
	v_mfma_f32_16x16x32_bf16 v[14:17], v[182:185], v[222:225], v[14:17]
	v_mfma_f32_16x16x32_bf16 v[10:13], v[186:189], v[218:221], v[10:13]
	s_barrier
	v_mfma_f32_16x16x32_bf16 v[10:13], v[190:193], v[222:225], v[10:13]
	s_setprio 0
	s_add_u32 s24, s48, 0x40080
	s_addc_u32 s25, s49, 0
	s_add_i32 s39, s51, s94
	s_mov_b32 m0, s39
	s_nop 0
	global_load_lds_dwordx4 v134, s[24:25]
	s_add_i32 m0, s39, 0x2000
	s_nop 0
	global_load_lds_dwordx4 v130, s[24:25]
	s_waitcnt vmcnt(6)
	s_barrier
	s_setprio 1
	v_mfma_f32_16x16x32_bf16 v[54:57], v[226:229], v[194:197], v[54:57]
	ds_read_b128 v[142:145], v249
	ds_read_b128 v[182:185], v249 offset:1024
	v_mfma_f32_16x16x32_bf16 v[54:57], v[230:233], v[198:201], v[54:57]
	ds_read_b128 v[186:189], v249 offset:2048
	ds_read_b128 v[190:193], v249 offset:3072
	v_mfma_f32_16x16x32_bf16 v[50:53], v[234:237], v[194:197], v[50:53]
	ds_read_b128 v[194:197], v166
	v_mfma_f32_16x16x32_bf16 v[50:53], v[238:241], v[198:201], v[50:53]
	ds_read_b128 v[198:201], v166 offset:1024
	v_mfma_f32_16x16x32_bf16 v[38:41], v[226:229], v[202:205], v[38:41]
	v_mfma_f32_16x16x32_bf16 v[38:41], v[230:233], v[206:209], v[38:41]
	v_mfma_f32_16x16x32_bf16 v[34:37], v[234:237], v[202:205], v[34:37]
	ds_read_b128 v[202:205], v166 offset:2048
	v_mfma_f32_16x16x32_bf16 v[34:37], v[238:241], v[206:209], v[34:37]
	ds_read_b128 v[206:209], v166 offset:3072
	v_mfma_f32_16x16x32_bf16 v[22:25], v[226:229], v[210:213], v[22:25]
	v_mfma_f32_16x16x32_bf16 v[22:25], v[230:233], v[214:217], v[22:25]
	v_mfma_f32_16x16x32_bf16 v[18:21], v[234:237], v[210:213], v[18:21]
	ds_read_b128 v[210:213], v166 offset:4096
	v_mfma_f32_16x16x32_bf16 v[18:21], v[238:241], v[214:217], v[18:21]
	ds_read_b128 v[214:217], v166 offset:5120
	v_mfma_f32_16x16x32_bf16 v[6:9], v[226:229], v[218:221], v[6:9]
	v_mfma_f32_16x16x32_bf16 v[6:9], v[230:233], v[222:225], v[6:9]
	v_mfma_f32_16x16x32_bf16 v[2:5], v[234:237], v[218:221], v[2:5]
	s_barrier
	v_mfma_f32_16x16x32_bf16 v[2:5], v[238:241], v[222:225], v[2:5]
	s_setprio 0
	s_add_i32 s38, s38, 2
	s_add_u32 s35, s35, 0x100
	s_addc_u32 s50, s50, 0
	s_add_u32 s0, s0, 0x100
	s_addc_u32 s1, s1, 0
	s_cmp_gt_u32 s38, 13

; #define PG8_STAGE(bufoff, gbase, voff) do { _Pragma("unroll") for (int _i = 0; _i < 2; ++_i) \
;         __builtin_amdgcn_global_load_lds((const unsigned*)((const char*)(gbase) + (voff)[_i]), (LAS unsigned*)(lds + (bufoff) + ldsw + _i * 8192), 16, 0, 0); } while (0)
; #define PG8_LDA(dst, b, h) do { _Pragma("unroll") for (int m = 0; m < 4; ++m) _Pragma("unroll") for (int k = 0; k < 2; ++k) dst[m][k] = *(const LAS bf16x8*)(lds + PG8_SA(b, h) + aoff + m * 2048 + k * 1024); } while (0)
; #define PG8_LDB(dst, b, h) do { _Pragma("unroll") for (int n = 0; n < 2; ++n) _Pragma("unroll") for (int k = 0; k < 2; ++k) dst[n][k] = *(const LAS bf16x8*)(lds + PG8_SB(b, h) + boff + n * 2048 + k * 1024); } while (0)
; #define PG8_WAIT_V(n) asm volatile("s_waitcnt vmcnt(" #n ")" ::: "memory")
; #define PG8_WAIT_L(n) asm volatile("s_waitcnt lgkmcnt(" #n ")" ::: "memory")
; #define PG8_BAR __builtin_amdgcn_s_barrier()
; #define PG8_SCHED __builtin_amdgcn_sched_barrier(0)
; template <class Epi, class Sched>
; __device__ __forceinline__ void gemm_phase(LAS unsigned char* lds, const Gemm g, const Sched& S, const Epi& E) {
;     ...
;         const bool has_next = S.next(ui + 1, nxt);
;         const char* nA = has_next ? PG8_APANEL(nxt.pm) : cA; const char* nB = has_next ? (const char*)g.Bt + (size_t)nxt.pn * tstep : cB;
;         for (int t = 0; t < nt; t += 2) {
;             const bool last = (t == nt - 2);
;             const char* a1 = cA + (size_t)(t + 1) * kstep;
;             const char* a2 = last ? nA : cA + (size_t)(t + 2) * kstep; const char* b2 = last ? nB : cB + (size_t)(t + 2) * kstep;
;             const char* a3 = a2 + kstep; const char* b3 = b2 + kstep;
;             PG8_LDB(B0, 0, 0); PG8_SCHED; PG8_LDA(At, 0, 0); PG8_STAGE(PG8_SA(1, 1), a1 + hstep, voffA);
;             PG8_WAIT_L(8); PG8_BAR; PG8_WAIT_L(0); PG8_MMA(0, 0, At, B0); PG8_BAR; PG8_SCHED;
;             PG8_LDB(B1, 0, 1); PG8_STAGE(PG8_SB(0, 0), b2, voffB);
;             PG8_BAR; PG8_WAIT_L(0); PG8_MMA(0, 1, At, B1); PG8_BAR;
;             PG8_LDA(At, 0, 1); PG8_STAGE(PG8_SA(0, 0), a2, voffA);
;             PG8_BAR; PG8_WAIT_L(0); PG8_MMA(1, 0, At, B0); PG8_BAR; PG8_SCHED;
;             PG8_STAGE(PG8_SB(0, 1), b2 + hstep, voffB);
;             PG8_WAIT_V(6); PG8_BAR; PG8_MMA(1, 1, At, B1); PG8_BAR;
.LBB0_626:
	s_ashr_i32 s43, s42, 31
	s_lshl_b64 s[24:25], s[42:43], 21
	s_add_u32 s60, s55, s24
	s_addc_u32 s61, s82, s25
	s_and_b64 s[0:1], s[0:1], exec
	s_cselect_b32 s43, s61, s49
	s_cselect_b32 s45, s60, s48
	s_add_u32 s35, s48, 0x100
	s_addc_u32 s50, s49, 0
	s_add_u32 s0, s76, 0x100080
	s_addc_u32 s1, s77, 0
	s_mov_b32 s98, -2
	v_add_u32_e32 v249, 0x10000, v144
	ds_read_b128 v[164:167], v249
	ds_read_b128 v[182:185], v249 offset:1024
	ds_read_b128 v[186:189], v249 offset:2048
	ds_read_b128 v[190:193], v249 offset:3072
	ds_read_b128 v[194:197], v162
	ds_read_b128 v[198:201], v162 offset:1024
	ds_read_b128 v[202:205], v162 offset:2048
	ds_read_b128 v[206:209], v162 offset:3072
	ds_read_b128 v[210:213], v162 offset:4096
	ds_read_b128 v[214:217], v162 offset:5120
	s_add_u32 s24, s0, 0xfff00080
	s_addc_u32 s25, s1, -1
	s_add_i32 s51, 0, 0x10000
	s_cmp_eq_u32 s98, 60
	s_cselect_b32 s77, s47, s25
	s_cselect_b32 s76, s46, s24
	s_cselect_b32 s49, s43, s50
	s_cselect_b32 s48, s45, s35
	s_add_i32 m0, s86, 0xc000
	ds_read_b128 v[218:221], v162 offset:6144
	ds_read_b128 v[222:225], v162 offset:7168
	global_load_lds_dwordx4 v140, s[0:1]
	s_add_i32 m0, s86, 0xe000
	s_nop 0
	global_load_lds_dwordx4 v138, s[0:1]
	s_waitcnt lgkmcnt(8)
	s_barrier
	s_waitcnt lgkmcnt(0)
	s_setprio 1
	s_waitcnt lgkmcnt(0)
	v_mfma_f32_16x16x32_bf16 v[126:129], v[164:167], v[194:197], 0
	v_mfma_f32_16x16x32_bf16 v[126:129], v[182:185], v[198:201], v[126:129]
	v_mfma_f32_16x16x32_bf16 v[122:125], v[186:189], v[194:197], 0
	v_mfma_f32_16x16x32_bf16 v[122:125], v[190:193], v[198:201], v[122:125]
	v_mfma_f32_16x16x32_bf16 v[118:121], v[164:167], v[202:205], 0
	v_mfma_f32_16x16x32_bf16 v[118:121], v[182:185], v[206:209], v[118:121]
	v_mfma_f32_16x16x32_bf16 v[110:113], v[186:189], v[202:205], 0
	v_mfma_f32_16x16x32_bf16 v[110:113], v[190:193], v[206:209], v[110:113]
	v_mfma_f32_16x16x32_bf16 v[102:105], v[164:167], v[210:213], 0
	v_mfma_f32_16x16x32_bf16 v[102:105], v[182:185], v[214:217], v[102:105]
	v_mfma_f32_16x16x32_bf16 v[94:97], v[186:189], v[210:213], 0
	v_mfma_f32_16x16x32_bf16 v[94:97], v[190:193], v[214:217], v[94:97]
	v_mfma_f32_16x16x32_bf16 v[86:89], v[164:167], v[218:221], 0
	v_mfma_f32_16x16x32_bf16 v[86:89], v[182:185], v[222:225], v[86:89]
	v_mfma_f32_16x16x32_bf16 v[78:81], v[186:189], v[218:221], 0
	s_barrier
	v_mfma_f32_16x16x32_bf16 v[78:81], v[190:193], v[222:225], v[78:81]
	s_setprio 0
	s_add_i32 s99, 0, 0x14000
	s_add_i32 s24, s51, s83
	ds_read_b128 v[226:229], v249 offset:16384
	ds_read_b128 v[230:233], v249 offset:17408
	ds_read_b128 v[234:237], v249 offset:18432
	ds_read_b128 v[238:241], v249 offset:19456
	s_mov_b32 m0, s24
	global_load_lds_dwordx4 v134, s[48:49]
	s_add_i32 m0, s24, 0x2000
	s_nop 0
	global_load_lds_dwordx4 v130, s[48:49]
	s_barrier
	s_waitcnt lgkmcnt(0)
	s_setprio 1
	s_waitcnt lgkmcnt(0)
	v_mfma_f32_16x16x32_bf16 v[114:117], v[226:229], v[194:197], 0
	v_mfma_f32_16x16x32_bf16 v[114:117], v[230:233], v[198:201], v[114:117]
	v_mfma_f32_16x16x32_bf16 v[106:109], v[234:237], v[194:197], 0
	v_mfma_f32_16x16x32_bf16 v[106:109], v[238:241], v[198:201], v[106:109]
	v_mfma_f32_16x16x32_bf16 v[98:101], v[226:229], v[202:205], 0
	v_mfma_f32_16x16x32_bf16 v[98:101], v[230:233], v[206:209], v[98:101]
	v_mfma_f32_16x16x32_bf16 v[90:93], v[234:237], v[202:205], 0
	v_mfma_f32_16x16x32_bf16 v[90:93], v[238:241], v[206:209], v[90:93]
	v_mfma_f32_16x16x32_bf16 v[82:85], v[226:229], v[210:213], 0
	v_mfma_f32_16x16x32_bf16 v[82:85], v[230:233], v[214:217], v[82:85]
	v_mfma_f32_16x16x32_bf16 v[74:77], v[234:237], v[210:213], 0
	v_mfma_f32_16x16x32_bf16 v[74:77], v[238:241], v[214:217], v[74:77]
	v_mfma_f32_16x16x32_bf16 v[70:73], v[226:229], v[218:221], 0
	v_mfma_f32_16x16x32_bf16 v[70:73], v[230:233], v[222:225], v[70:73]
	v_mfma_f32_16x16x32_bf16 v[66:69], v[234:237], v[218:221], 0
	s_barrier
	v_mfma_f32_16x16x32_bf16 v[66:69], v[238:241], v[222:225], v[66:69]
	s_setprio 0
	s_mov_b32 m0, s86
	s_mov_b64 s[100:101], s[76:77]
	ds_read_b128 v[194:197], v162 offset:16384
	ds_read_b128 v[198:201], v162 offset:17408
	ds_read_b128 v[202:205], v162 offset:18432
	ds_read_b128 v[206:209], v162 offset:19456
	ds_read_b128 v[210:213], v162 offset:20480
	ds_read_b128 v[214:217], v162 offset:21504
	ds_read_b128 v[218:221], v162 offset:22528
	ds_read_b128 v[222:225], v162 offset:23552
	global_load_lds_dwordx4 v136, s[76:77]
	s_mov_b64 s[100:101], s[76:77]
	s_mov_b32 m0, s92
	s_nop 0
	global_load_lds_dwordx4 v132, s[76:77]
	s_waitcnt vmcnt(8)
	s_barrier
	s_waitcnt lgkmcnt(0)
	s_setprio 1
	s_waitcnt lgkmcnt(0)
	v_mfma_f32_16x16x32_bf16 v[62:65], v[164:167], v[194:197], 0
	v_mfma_f32_16x16x32_bf16 v[62:65], v[182:185], v[198:201], v[62:65]
	v_mfma_f32_16x16x32_bf16 v[58:61], v[186:189], v[194:197], 0
	v_mfma_f32_16x16x32_bf16 v[58:61], v[190:193], v[198:201], v[58:61]
	v_mfma_f32_16x16x32_bf16 v[54:57], v[164:167], v[202:205], 0
	v_mfma_f32_16x16x32_bf16 v[54:57], v[182:185], v[206:209], v[54:57]
	v_mfma_f32_16x16x32_bf16 v[46:49], v[186:189], v[202:205], 0
	v_mfma_f32_16x16x32_bf16 v[46:49], v[190:193], v[206:209], v[46:49]
	v_mfma_f32_16x16x32_bf16 v[38:41], v[164:167], v[210:213], 0
	v_mfma_f32_16x16x32_bf16 v[38:41], v[182:185], v[214:217], v[38:41]
	v_mfma_f32_16x16x32_bf16 v[30:33], v[186:189], v[210:213], 0
	v_mfma_f32_16x16x32_bf16 v[30:33], v[190:193], v[214:217], v[30:33]
	v_mfma_f32_16x16x32_bf16 v[22:25], v[164:167], v[218:221], 0
	v_mfma_f32_16x16x32_bf16 v[22:25], v[182:185], v[222:225], v[22:25]
	v_mfma_f32_16x16x32_bf16 v[14:17], v[186:189], v[218:221], 0
	s_barrier
; #define PG8_STAGE(bufoff, gbase, voff) do { _Pragma("unroll") for (int _i = 0; _i < 2; ++_i) \
;         __builtin_amdgcn_global_load_lds((const unsigned*)((const char*)(gbase) + (voff)[_i]), (LAS unsigned*)(lds + (bufoff) + ldsw + _i * 8192), 16, 0, 0); } while (0)
; #define PG8_LDA(dst, b, h) do { _Pragma("unroll") for (int m = 0; m < 4; ++m) _Pragma("unroll") for (int k = 0; k < 2; ++k) dst[m][k] = *(const LAS bf16x8*)(lds + PG8_SA(b, h) + aoff + m * 2048 + k * 1024); } while (0)
; #define PG8_LDB(dst, b, h) do { _Pragma("unroll") for (int n = 0; n < 2; ++n) _Pragma("unroll") for (int k = 0; k < 2; ++k) dst[n][k] = *(const LAS bf16x8*)(lds + PG8_SB(b, h) + boff + n * 2048 + k * 1024); } while (0)
; #define PG8_MMA(ai, bj, At, Bt) do { __builtin_amdgcn_s_setprio(1); _Pragma("unroll") for (int m = 0; m < 4; ++m) _Pragma("unroll") for (int n = 0; n < 2; ++n) _Pragma("unroll") for (int k = 0; k < 2; ++k) \
;         acc[ai][bj][m][n] = __builtin_amdgcn_mfma_f32_16x16x32_bf16(Bt[n][k], At[m][k], acc[ai][bj][m][n], 0, 0, 0); __builtin_amdgcn_s_setprio(0); } while (0)
; #define PG8_WAIT_V(n) asm volatile("s_waitcnt vmcnt(" #n ")" ::: "memory")
; #define PG8_WAIT_L(n) asm volatile("s_waitcnt lgkmcnt(" #n ")" ::: "memory")
; #define PG8_BAR __builtin_amdgcn_s_barrier()
; #define PG8_SCHED __builtin_amdgcn_sched_barrier(0)
; template <class Epi, class Sched>
; __device__ __forceinline__ void gemm_phase(LAS unsigned char* lds, const Gemm g, const Sched& S, const Epi& E) {
;     ...
;             PG8_WAIT_V(6); PG8_BAR; PG8_MMA(1, 1, At, B1); PG8_BAR;
;             PG8_LDB(B0, 1, 0); PG8_SCHED; PG8_LDA(At, 1, 0); PG8_STAGE(PG8_SA(0, 1), a2 + hstep, voffA);
;             PG8_WAIT_L(8); PG8_BAR; PG8_WAIT_L(0); PG8_MMA(0, 0, At, B0); PG8_BAR; PG8_SCHED;
;             PG8_LDB(B1, 1, 1); PG8_STAGE(PG8_SB(1, 0), b3, voffB);
;             PG8_BAR; PG8_WAIT_L(0); PG8_MMA(0, 1, At, B1); PG8_BAR;
;             PG8_LDA(At, 1, 1); PG8_STAGE(PG8_SA(1, 0), a3, voffA);
;             PG8_BAR; PG8_WAIT_L(0); PG8_MMA(1, 0, At, B0); PG8_BAR; PG8_SCHED;
	v_mfma_f32_16x16x32_bf16 v[14:17], v[190:193], v[222:225], v[14:17]
	s_setprio 0
	s_add_u32 s24, s48, 0x100000
	s_addc_u32 s25, s49, 0
	s_add_i32 s51, s99, s83
	s_mov_b32 m0, s51
	s_nop 0
	global_load_lds_dwordx4 v134, s[24:25]
	s_add_i32 m0, s51, 0x2000
	s_nop 0
	global_load_lds_dwordx4 v130, s[24:25]
	s_waitcnt vmcnt(6)
	s_barrier
	s_setprio 1
	v_mfma_f32_16x16x32_bf16 v[50:53], v[226:229], v[194:197], 0
	ds_read_b128 v[164:167], v249 offset:32768
	ds_read_b128 v[182:185], v249 offset:33792
	v_mfma_f32_16x16x32_bf16 v[50:53], v[230:233], v[198:201], v[50:53]
	ds_read_b128 v[186:189], v249 offset:34816
	ds_read_b128 v[190:193], v249 offset:35840
	v_mfma_f32_16x16x32_bf16 v[42:45], v[234:237], v[194:197], 0
	ds_read_b128 v[194:197], v162 offset:32768
	v_mfma_f32_16x16x32_bf16 v[42:45], v[238:241], v[198:201], v[42:45]
	ds_read_b128 v[198:201], v162 offset:33792
	v_mfma_f32_16x16x32_bf16 v[34:37], v[226:229], v[202:205], 0
	v_mfma_f32_16x16x32_bf16 v[34:37], v[230:233], v[206:209], v[34:37]
	v_mfma_f32_16x16x32_bf16 v[26:29], v[234:237], v[202:205], 0
	ds_read_b128 v[202:205], v162 offset:34816
	v_mfma_f32_16x16x32_bf16 v[26:29], v[238:241], v[206:209], v[26:29]
	ds_read_b128 v[206:209], v162 offset:35840
	v_mfma_f32_16x16x32_bf16 v[18:21], v[226:229], v[210:213], 0
	v_mfma_f32_16x16x32_bf16 v[18:21], v[230:233], v[214:217], v[18:21]
	v_mfma_f32_16x16x32_bf16 v[10:13], v[234:237], v[210:213], 0
	ds_read_b128 v[210:213], v162 offset:36864
	v_mfma_f32_16x16x32_bf16 v[10:13], v[238:241], v[214:217], v[10:13]
	ds_read_b128 v[214:217], v162 offset:37888
	v_mfma_f32_16x16x32_bf16 v[6:9], v[226:229], v[218:221], 0
	v_mfma_f32_16x16x32_bf16 v[6:9], v[230:233], v[222:225], v[6:9]
	v_mfma_f32_16x16x32_bf16 v[2:5], v[234:237], v[218:221], 0
	s_barrier
	v_mfma_f32_16x16x32_bf16 v[2:5], v[238:241], v[222:225], v[2:5]
	s_setprio 0
	s_add_i32 s51, 0, 0x18000
	s_add_u32 s24, s76, 0x100000
	s_addc_u32 s25, s77, 0
	s_mov_b32 m0, s93
	ds_read_b128 v[218:221], v162 offset:38912
	ds_read_b128 v[222:225], v162 offset:39936
	global_load_lds_dwordx4 v136, s[24:25]
	s_mov_b32 m0, s94
	s_nop 0
	global_load_lds_dwordx4 v132, s[24:25]
	s_waitcnt lgkmcnt(8)
	s_barrier
	s_waitcnt lgkmcnt(0)
	s_setprio 1
	s_waitcnt lgkmcnt(0)
	v_mfma_f32_16x16x32_bf16 v[126:129], v[164:167], v[194:197], v[126:129]
	v_mfma_f32_16x16x32_bf16 v[126:129], v[182:185], v[198:201], v[126:129]
	v_mfma_f32_16x16x32_bf16 v[122:125], v[186:189], v[194:197], v[122:125]
	v_mfma_f32_16x16x32_bf16 v[122:125], v[190:193], v[198:201], v[122:125]
	v_mfma_f32_16x16x32_bf16 v[118:121], v[164:167], v[202:205], v[118:121]
	v_mfma_f32_16x16x32_bf16 v[118:121], v[182:185], v[206:209], v[118:121]
	v_mfma_f32_16x16x32_bf16 v[110:113], v[186:189], v[202:205], v[110:113]
	v_mfma_f32_16x16x32_bf16 v[110:113], v[190:193], v[206:209], v[110:113]
	v_mfma_f32_16x16x32_bf16 v[102:105], v[164:167], v[210:213], v[102:105]
	v_mfma_f32_16x16x32_bf16 v[102:105], v[182:185], v[214:217], v[102:105]
	v_mfma_f32_16x16x32_bf16 v[94:97], v[186:189], v[210:213], v[94:97]
	v_mfma_f32_16x16x32_bf16 v[94:97], v[190:193], v[214:217], v[94:97]
	v_mfma_f32_16x16x32_bf16 v[86:89], v[164:167], v[218:221], v[86:89]
	v_mfma_f32_16x16x32_bf16 v[86:89], v[182:185], v[222:225], v[86:89]
	v_mfma_f32_16x16x32_bf16 v[78:81], v[186:189], v[218:221], v[78:81]
	s_barrier
	v_mfma_f32_16x16x32_bf16 v[78:81], v[190:193], v[222:225], v[78:81]
	s_setprio 0
	s_add_i32 s76, 0, 0x1c000
	s_add_i32 s24, s51, s83
	s_add_i32 m0, s24, 0xffffff80
	ds_read_b128 v[226:229], v249 offset:49152
	ds_read_b128 v[230:233], v249 offset:50176
	ds_read_b128 v[234:237], v249 offset:51200
	ds_read_b128 v[238:241], v249 offset:52224
	global_load_lds_dwordx4 v134, s[48:49] offset:128
	s_add_i32 m0, s24, 0x1f80
	s_nop 0
	global_load_lds_dwordx4 v130, s[48:49] offset:128
	s_barrier
; #define PG8_STAGE(bufoff, gbase, voff) do { _Pragma("unroll") for (int _i = 0; _i < 2; ++_i) \
;         __builtin_amdgcn_global_load_lds((const unsigned*)((const char*)(gbase) + (voff)[_i]), (LAS unsigned*)(lds + (bufoff) + ldsw + _i * 8192), 16, 0, 0); } while (0)
; #define PG8_LDA(dst, b, h) do { _Pragma("unroll") for (int m = 0; m < 4; ++m) _Pragma("unroll") for (int k = 0; k < 2; ++k) dst[m][k] = *(const LAS bf16x8*)(lds + PG8_SA(b, h) + aoff + m * 2048 + k * 1024); } while (0)
; #define PG8_LDB(dst, b, h) do { _Pragma("unroll") for (int n = 0; n < 2; ++n) _Pragma("unroll") for (int k = 0; k < 2; ++k) dst[n][k] = *(const LAS bf16x8*)(lds + PG8_SB(b, h) + boff + n * 2048 + k * 1024); } while (0)
; #define PG8_MMA(ai, bj, At, Bt) do { __builtin_amdgcn_s_setprio(1); _Pragma("unroll") for (int m = 0; m < 4; ++m) _Pragma("unroll") for (int n = 0; n < 2; ++n) _Pragma("unroll") for (int k = 0; k < 2; ++k) \
;         acc[ai][bj][m][n] = __builtin_amdgcn_mfma_f32_16x16x32_bf16(Bt[n][k], At[m][k], acc[ai][bj][m][n], 0, 0, 0); __builtin_amdgcn_s_setprio(0); } while (0)
; #define PG8_WAIT_V(n) asm volatile("s_waitcnt vmcnt(" #n ")" ::: "memory")
; #define PG8_WAIT_L(n) asm volatile("s_waitcnt lgkmcnt(" #n ")" ::: "memory")
; #define PG8_BAR __builtin_amdgcn_s_barrier()
; #define PG8_SCHED __builtin_amdgcn_sched_barrier(0)
; template <class Epi, class Sched>
; __device__ __forceinline__ void gemm_phase(LAS unsigned char* lds, const Gemm g, const Sched& S, const Epi& E) {
;     ...
;             PG8_WAIT_L(8); PG8_BAR; PG8_WAIT_L(0); PG8_MMA(0, 0, At, B0); PG8_BAR; PG8_SCHED;
;             PG8_LDB(B1, 1, 1); PG8_STAGE(PG8_SB(1, 0), b3, voffB);
;             PG8_BAR; PG8_WAIT_L(0); PG8_MMA(0, 1, At, B1); PG8_BAR;
;             PG8_LDA(At, 1, 1); PG8_STAGE(PG8_SA(1, 0), a3, voffA);
;             PG8_BAR; PG8_WAIT_L(0); PG8_MMA(1, 0, At, B0); PG8_BAR; PG8_SCHED;
;             PG8_STAGE(PG8_SB(1, 1), b3 + hstep, voffB);
;             PG8_WAIT_V(6); PG8_BAR; PG8_MMA(1, 1, At, B1); PG8_BAR;
;         }
	s_waitcnt lgkmcnt(0)
	s_setprio 1
	s_waitcnt lgkmcnt(0)
	v_mfma_f32_16x16x32_bf16 v[114:117], v[226:229], v[194:197], v[114:117]
	v_mfma_f32_16x16x32_bf16 v[114:117], v[230:233], v[198:201], v[114:117]
	v_mfma_f32_16x16x32_bf16 v[106:109], v[234:237], v[194:197], v[106:109]
	v_mfma_f32_16x16x32_bf16 v[106:109], v[238:241], v[198:201], v[106:109]
	v_mfma_f32_16x16x32_bf16 v[98:101], v[226:229], v[202:205], v[98:101]
	v_mfma_f32_16x16x32_bf16 v[98:101], v[230:233], v[206:209], v[98:101]
	v_mfma_f32_16x16x32_bf16 v[90:93], v[234:237], v[202:205], v[90:93]
	v_mfma_f32_16x16x32_bf16 v[90:93], v[238:241], v[206:209], v[90:93]
	v_mfma_f32_16x16x32_bf16 v[82:85], v[226:229], v[210:213], v[82:85]
	v_mfma_f32_16x16x32_bf16 v[82:85], v[230:233], v[214:217], v[82:85]
	v_mfma_f32_16x16x32_bf16 v[74:77], v[234:237], v[210:213], v[74:77]
	v_mfma_f32_16x16x32_bf16 v[74:77], v[238:241], v[214:217], v[74:77]
	v_mfma_f32_16x16x32_bf16 v[70:73], v[226:229], v[218:221], v[70:73]
	v_mfma_f32_16x16x32_bf16 v[70:73], v[230:233], v[222:225], v[70:73]
	v_mfma_f32_16x16x32_bf16 v[66:69], v[234:237], v[218:221], v[66:69]
	s_barrier
	v_mfma_f32_16x16x32_bf16 v[66:69], v[238:241], v[222:225], v[66:69]
	s_setprio 0
	s_add_i32 m0, s95, 0xffffff80
	ds_read_b128 v[194:197], v162 offset:49152
	ds_read_b128 v[198:201], v162 offset:50176
	ds_read_b128 v[202:205], v162 offset:51200
	ds_read_b128 v[206:209], v162 offset:52224
	ds_read_b128 v[210:213], v162 offset:53248
	ds_read_b128 v[214:217], v162 offset:54272
	ds_read_b128 v[218:221], v162 offset:55296
	ds_read_b128 v[222:225], v162 offset:56320
	global_load_lds_dwordx4 v136, s[100:101] offset:128
	s_add_i32 m0, s96, 0xffffff80
	s_nop 0
	global_load_lds_dwordx4 v132, s[100:101] offset:128
	s_waitcnt vmcnt(8)
	s_barrier
	s_waitcnt lgkmcnt(0)
	s_setprio 1
	s_waitcnt lgkmcnt(0)
	v_mfma_f32_16x16x32_bf16 v[62:65], v[164:167], v[194:197], v[62:65]
	v_mfma_f32_16x16x32_bf16 v[62:65], v[182:185], v[198:201], v[62:65]
	v_mfma_f32_16x16x32_bf16 v[58:61], v[186:189], v[194:197], v[58:61]
	v_mfma_f32_16x16x32_bf16 v[58:61], v[190:193], v[198:201], v[58:61]
	v_mfma_f32_16x16x32_bf16 v[54:57], v[164:167], v[202:205], v[54:57]
	v_mfma_f32_16x16x32_bf16 v[54:57], v[182:185], v[206:209], v[54:57]
	v_mfma_f32_16x16x32_bf16 v[46:49], v[186:189], v[202:205], v[46:49]
	v_mfma_f32_16x16x32_bf16 v[46:49], v[190:193], v[206:209], v[46:49]
	v_mfma_f32_16x16x32_bf16 v[38:41], v[164:167], v[210:213], v[38:41]
	v_mfma_f32_16x16x32_bf16 v[38:41], v[182:185], v[214:217], v[38:41]
	v_mfma_f32_16x16x32_bf16 v[30:33], v[186:189], v[210:213], v[30:33]
	v_mfma_f32_16x16x32_bf16 v[30:33], v[190:193], v[214:217], v[30:33]
	v_mfma_f32_16x16x32_bf16 v[22:25], v[164:167], v[218:221], v[22:25]
	v_mfma_f32_16x16x32_bf16 v[22:25], v[182:185], v[222:225], v[22:25]
	v_mfma_f32_16x16x32_bf16 v[14:17], v[186:189], v[218:221], v[14:17]
	s_barrier
	v_mfma_f32_16x16x32_bf16 v[14:17], v[190:193], v[222:225], v[14:17]
	s_setprio 0
	s_add_u32 s24, s48, 0x100080
	s_addc_u32 s25, s49, 0
	s_add_i32 s48, s76, s83
	s_mov_b32 m0, s48
	s_nop 0
	global_load_lds_dwordx4 v134, s[24:25]
	s_add_i32 m0, s48, 0x2000
	s_nop 0
	global_load_lds_dwordx4 v130, s[24:25]
	s_waitcnt vmcnt(6)
	s_barrier
	s_setprio 1
	v_mfma_f32_16x16x32_bf16 v[50:53], v[226:229], v[194:197], v[50:53]
	ds_read_b128 v[164:167], v249
	ds_read_b128 v[182:185], v249 offset:1024
	v_mfma_f32_16x16x32_bf16 v[50:53], v[230:233], v[198:201], v[50:53]
	ds_read_b128 v[186:189], v249 offset:2048
	ds_read_b128 v[190:193], v249 offset:3072
	v_mfma_f32_16x16x32_bf16 v[42:45], v[234:237], v[194:197], v[42:45]
	ds_read_b128 v[194:197], v162
	v_mfma_f32_16x16x32_bf16 v[42:45], v[238:241], v[198:201], v[42:45]
	ds_read_b128 v[198:201], v162 offset:1024
	v_mfma_f32_16x16x32_bf16 v[34:37], v[226:229], v[202:205], v[34:37]
	v_mfma_f32_16x16x32_bf16 v[34:37], v[230:233], v[206:209], v[34:37]
	v_mfma_f32_16x16x32_bf16 v[26:29], v[234:237], v[202:205], v[26:29]
	ds_read_b128 v[202:205], v162 offset:2048
	v_mfma_f32_16x16x32_bf16 v[26:29], v[238:241], v[206:209], v[26:29]
	ds_read_b128 v[206:209], v162 offset:3072
	v_mfma_f32_16x16x32_bf16 v[18:21], v[226:229], v[210:213], v[18:21]
	v_mfma_f32_16x16x32_bf16 v[18:21], v[230:233], v[214:217], v[18:21]
	v_mfma_f32_16x16x32_bf16 v[10:13], v[234:237], v[210:213], v[10:13]
	ds_read_b128 v[210:213], v162 offset:4096
	v_mfma_f32_16x16x32_bf16 v[10:13], v[238:241], v[214:217], v[10:13]
	ds_read_b128 v[214:217], v162 offset:5120
	v_mfma_f32_16x16x32_bf16 v[6:9], v[226:229], v[218:221], v[6:9]
	v_mfma_f32_16x16x32_bf16 v[6:9], v[230:233], v[222:225], v[6:9]
	v_mfma_f32_16x16x32_bf16 v[2:5], v[234:237], v[218:221], v[2:5]
	s_barrier
	v_mfma_f32_16x16x32_bf16 v[2:5], v[238:241], v[222:225], v[2:5]
	s_setprio 0
	s_add_i32 s98, s98, 2
	s_add_u32 s35, s35, 0x100
	s_addc_u32 s50, s50, 0
	s_add_u32 s0, s0, 0x100
	s_addc_u32 s1, s1, 0
	s_cmp_gt_u32 s98, 61
